# combined: v20 + prologue de-serialisation + deeper wr0 re-sync barrier + boundary priority for waves 4-7 + nt hints on f32 residual traffic
# baseline (speedup 1.0000x reference)
; #define PG8_STAGE(bufoff, gbase, voff) do { _Pragma("unroll") for (int _i = 0; _i < 2; ++_i) \
;         __builtin_amdgcn_global_load_lds((const unsigned*)((const char*)(gbase) + (voff)[_i]), (LAS unsigned*)(lds + (bufoff) + ldsw + _i * 8192), 16, 0, 0); } while (0)
; #define PG8_LDA(dst, b, h) do { _Pragma("unroll") for (int m = 0; m < 4; ++m) _Pragma("unroll") for (int k = 0; k < 2; ++k) dst[m][k] = *(const LAS bf16x8*)(lds + PG8_SA(b, h) + aoff + m * 2048 + k * 1024); } while (0)
; #define PG8_LDB(dst, b, h) do { _Pragma("unroll") for (int n = 0; n < 2; ++n) _Pragma("unroll") for (int k = 0; k < 2; ++k) dst[n][k] = *(const LAS bf16x8*)(lds + PG8_SB(b, h) + boff + n * 2048 + k * 1024); } while (0)
; #define PG8_MMA(ai, bj, At, Bt) do { __builtin_amdgcn_s_setprio(1); _Pragma("unroll") for (int m = 0; m < 4; ++m) _Pragma("unroll") for (int n = 0; n < 2; ++n) _Pragma("unroll") for (int k = 0; k < 2; ++k) \
;         acc[ai][bj][m][n] = __builtin_amdgcn_mfma_f32_16x16x32_bf16(Bt[n][k], At[m][k], acc[ai][bj][m][n], 0, 0, 0); __builtin_amdgcn_s_setprio(0); } while (0)
; #define PG8_WAIT_V(n) asm volatile("s_waitcnt vmcnt(" #n ")" ::: "memory")
; #define PG8_WAIT_L(n) asm volatile("s_waitcnt lgkmcnt(" #n ")" ::: "memory")
; template <class Epi>
; __device__ __forceinline__ void gemm_phase(LAS unsigned char* lds, const Gemm g, const Sched& S, const Epi& E) {
;     ...
;         for (int t = 0; t < nt; t += 2) {
;             const bool last = (t == nt - 2);
;             const char* a1 = cA + (size_t)(t + 1) * kstep;
;             const char* a2 = last ? nA : cA + (size_t)(t + 2) * kstep; const char* b2 = last ? nB : cB + (size_t)(t + 2) * kstep;
;             const char* a3 = a2 + kstep; const char* b3 = b2 + kstep;
;             PG8_LDB(B0, 0, 0); PG8_SCHED; PG8_LDA(At, 0, 0); PG8_STAGE(PG8_SA(1, 1), a1 + hstepA, voffA);
;             PG8_WAIT_L(8); PG8_BAR; PG8_WAIT_L(0); PG8_MMA(0, 0, At, B0); PG8_BAR; PG8_SCHED;
;             PG8_LDB(B1, 0, 1); PG8_STAGE(PG8_SB(0, 0), b2, voffB);
;             PG8_BAR; PG8_WAIT_L(0); PG8_MMA(0, 1, At, B1); PG8_BAR;
;             PG8_LDA(At, 0, 1); PG8_STAGE(PG8_SA(0, 0), a2, voffA);
;             PG8_BAR; PG8_WAIT_L(0); PG8_MMA(1, 0, At, B0); PG8_BAR; PG8_SCHED;
;             PG8_STAGE(PG8_SB(0, 1), b2 + hstepB, voffB);
;             PG8_WAIT_V(6); PG8_BAR; PG8_MMA(1, 1, At, B1); PG8_BAR;
.Lresync_y_400:
.LBB0_400:
	s_add_i32 s14, s66, 2
	s_add_u32 s8, s92, 0x80
	s_addc_u32 s9, s93, 0
	s_add_i32 s15, 0, 0x10000
	v_add_u32_e32 v148, s15, v152
	ds_read_b128 v[144:147], v148
	ds_read_b128 v[172:175], v148 offset:1024
	ds_read_b128 v[176:179], v148 offset:2048
	ds_read_b128 v[180:183], v148 offset:3072
	s_cmp_eq_u32 s71, s66
	s_cselect_b32 s95, s55, s9
	s_cselect_b32 s94, s57, s8
	s_cselect_b32 s97, s59, s35
	s_cselect_b32 s96, s65, s34
	v_lshl_add_u64 v[148:149], s[92:93], 0, v[138:139]
	s_add_i32 m0, s42, 0xc000
	ds_read_b128 v[184:187], v171
	ds_read_b128 v[188:191], v171 offset:1024
	ds_read_b128 v[196:199], v171 offset:2048
	ds_read_b128 v[200:203], v171 offset:3072
	ds_read_b128 v[204:207], v171 offset:4096
	ds_read_b128 v[208:211], v171 offset:5120
	ds_read_b128 v[212:215], v171 offset:6144
	ds_read_b128 v[222:225], v171 offset:7168
	global_load_lds_dwordx4 v[148:149], off
	v_lshl_add_u64 v[148:149], s[92:93], 0, v[140:141]
	s_add_i32 m0, s42, 0xe000
	s_nop 0
	global_load_lds_dwordx4 v[148:149], off
	s_add_i32 s8, 0, 0x14000
	v_add_u32_e32 v148, s8, v152
	ds_read_b128 v[226:229], v148
	ds_read_b128 v[230:233], v148 offset:1024
	ds_read_b128 v[234:237], v148 offset:2048
	ds_read_b128 v[238:241], v148 offset:3072
	s_waitcnt vmcnt(8)
	s_waitcnt lgkmcnt(0)
	v_mfma_f32_16x16x32_bf16 v[126:129], v[144:147], v[184:187], v[126:129]
	v_mfma_f32_16x16x32_bf16 v[122:125], v[176:179], v[184:187], v[122:125]
	v_mfma_f32_16x16x32_bf16 v[110:113], v[144:147], v[196:199], v[110:113]
	v_mfma_f32_16x16x32_bf16 v[106:109], v[176:179], v[196:199], v[106:109]
	s_barrier
	s_setprio 1
	v_mfma_f32_16x16x32_bf16 v[94:97], v[144:147], v[204:207], v[94:97]
	v_mfma_f32_16x16x32_bf16 v[90:93], v[176:179], v[204:207], v[90:93]
	v_mfma_f32_16x16x32_bf16 v[78:81], v[144:147], v[212:215], v[78:81]
	v_mfma_f32_16x16x32_bf16 v[74:77], v[176:179], v[212:215], v[74:77]
	v_mfma_f32_16x16x32_bf16 v[126:129], v[172:175], v[188:191], v[126:129]
	v_mfma_f32_16x16x32_bf16 v[122:125], v[180:183], v[188:191], v[122:125]
	v_mfma_f32_16x16x32_bf16 v[110:113], v[172:175], v[200:203], v[110:113]
	v_mfma_f32_16x16x32_bf16 v[106:109], v[180:183], v[200:203], v[106:109]
	v_mfma_f32_16x16x32_bf16 v[94:97], v[172:175], v[208:211], v[94:97]
	v_mfma_f32_16x16x32_bf16 v[90:93], v[180:183], v[208:211], v[90:93]
	v_mfma_f32_16x16x32_bf16 v[78:81], v[172:175], v[222:225], v[78:81]
	v_mfma_f32_16x16x32_bf16 v[74:77], v[180:183], v[222:225], v[74:77]
	v_mfma_f32_16x16x32_bf16 v[118:121], v[226:229], v[184:187], v[118:121]
	v_mfma_f32_16x16x32_bf16 v[114:117], v[234:237], v[184:187], v[114:117]
	v_mfma_f32_16x16x32_bf16 v[102:105], v[226:229], v[196:199], v[102:105]
	v_mfma_f32_16x16x32_bf16 v[98:101], v[234:237], v[196:199], v[98:101]
	v_mfma_f32_16x16x32_bf16 v[86:89], v[226:229], v[204:207], v[86:89]
	v_mfma_f32_16x16x32_bf16 v[82:85], v[234:237], v[204:207], v[82:85]
	v_mfma_f32_16x16x32_bf16 v[70:73], v[226:229], v[212:215], v[70:73]
	v_mfma_f32_16x16x32_bf16 v[66:69], v[234:237], v[212:215], v[66:69]
	v_mfma_f32_16x16x32_bf16 v[118:121], v[230:233], v[188:191], v[118:121]
	v_mfma_f32_16x16x32_bf16 v[114:117], v[238:241], v[188:191], v[114:117]
	v_mfma_f32_16x16x32_bf16 v[102:105], v[230:233], v[200:203], v[102:105]
	v_mfma_f32_16x16x32_bf16 v[98:101], v[238:241], v[200:203], v[98:101]
	v_mfma_f32_16x16x32_bf16 v[86:89], v[230:233], v[208:211], v[86:89]
	v_mfma_f32_16x16x32_bf16 v[82:85], v[238:241], v[208:211], v[82:85]
	v_mfma_f32_16x16x32_bf16 v[70:73], v[230:233], v[222:225], v[70:73]
	v_mfma_f32_16x16x32_bf16 v[66:69], v[238:241], v[222:225], v[66:69]
	s_setprio 0
	s_barrier
	s_add_i32 s9, s15, s39
	v_lshl_add_u64 v[148:149], s[96:97], 0, v[132:133]
	s_mov_b32 m0, s9
	v_lshl_add_u64 v[192:193], s[96:97], 0, v[136:137]
	global_load_lds_dwordx4 v[148:149], off
	s_add_i32 m0, s9, 0x2000
	s_nop 0
	global_load_lds_dwordx4 v[192:193], off
	s_mov_b32 m0, s42
	v_lshl_add_u64 v[194:195], s[94:95], 0, v[130:131]
	ds_read_b128 v[184:187], v171 offset:16384
	ds_read_b128 v[188:191], v171 offset:17408
	ds_read_b128 v[196:199], v171 offset:18432
	ds_read_b128 v[200:203], v171 offset:19456
	ds_read_b128 v[204:207], v171 offset:20480
	ds_read_b128 v[208:211], v171 offset:21504
	ds_read_b128 v[212:215], v171 offset:22528
	ds_read_b128 v[222:225], v171 offset:23552
	global_load_lds_dwordx4 v[194:195], off
	v_lshl_add_u64 v[216:217], s[94:95], 0, v[134:135]
	s_mov_b32 m0, s43
	s_nop 0
	global_load_lds_dwordx4 v[216:217], off
	s_add_u32 s96, s96, s78
	s_addc_u32 s97, s97, s79
	s_add_i32 s8, s8, s39
	v_lshl_add_u64 v[242:243], s[96:97], 0, v[132:133]
	s_mov_b32 m0, s8
	v_lshl_add_u64 v[244:245], s[96:97], 0, v[136:137]
	global_load_lds_dwordx4 v[242:243], off
	s_add_i32 m0, s8, 0x2000
	s_nop 0
	global_load_lds_dwordx4 v[244:245], off
	s_waitcnt vmcnt(8)
	s_waitcnt lgkmcnt(0)
	v_mfma_f32_16x16x32_bf16 v[62:65], v[144:147], v[184:187], v[62:65]
	v_mfma_f32_16x16x32_bf16 v[58:61], v[176:179], v[184:187], v[58:61]
	v_mfma_f32_16x16x32_bf16 v[50:53], v[144:147], v[196:199], v[50:53]
	v_mfma_f32_16x16x32_bf16 v[42:45], v[176:179], v[196:199], v[42:45]
	s_barrier
; #define PG8_STAGE(bufoff, gbase, voff) do { _Pragma("unroll") for (int _i = 0; _i < 2; ++_i) \
;         __builtin_amdgcn_global_load_lds((const unsigned*)((const char*)(gbase) + (voff)[_i]), (LAS unsigned*)(lds + (bufoff) + ldsw + _i * 8192), 16, 0, 0); } while (0)
; #define PG8_LDA(dst, b, h) do { _Pragma("unroll") for (int m = 0; m < 4; ++m) _Pragma("unroll") for (int k = 0; k < 2; ++k) dst[m][k] = *(const LAS bf16x8*)(lds + PG8_SA(b, h) + aoff + m * 2048 + k * 1024); } while (0)
; #define PG8_LDB(dst, b, h) do { _Pragma("unroll") for (int n = 0; n < 2; ++n) _Pragma("unroll") for (int k = 0; k < 2; ++k) dst[n][k] = *(const LAS bf16x8*)(lds + PG8_SB(b, h) + boff + n * 2048 + k * 1024); } while (0)
; #define PG8_MMA(ai, bj, At, Bt) do { __builtin_amdgcn_s_setprio(1); _Pragma("unroll") for (int m = 0; m < 4; ++m) _Pragma("unroll") for (int n = 0; n < 2; ++n) _Pragma("unroll") for (int k = 0; k < 2; ++k) \
;         acc[ai][bj][m][n] = __builtin_amdgcn_mfma_f32_16x16x32_bf16(Bt[n][k], At[m][k], acc[ai][bj][m][n], 0, 0, 0); __builtin_amdgcn_s_setprio(0); } while (0)
; #define PG8_WAIT_V(n) asm volatile("s_waitcnt vmcnt(" #n ")" ::: "memory")
; #define PG8_WAIT_L(n) asm volatile("s_waitcnt lgkmcnt(" #n ")" ::: "memory")
; #define PG8_BAR __builtin_amdgcn_s_barrier()
; #define PG8_SCHED __builtin_amdgcn_sched_barrier(0)
; template <class Epi>
; __device__ __forceinline__ void gemm_phase(LAS unsigned char* lds, const Gemm g, const Sched& S, const Epi& E) {
;     ...
;             PG8_WAIT_V(6); PG8_BAR; PG8_MMA(1, 1, At, B1); PG8_BAR;
;             PG8_LDB(B0, 1, 0); PG8_SCHED; PG8_LDA(At, 1, 0); PG8_STAGE(PG8_SA(0, 1), a2 + hstepA, voffA);
;             PG8_WAIT_L(8); PG8_BAR; PG8_WAIT_L(0); PG8_MMA(0, 0, At, B0); PG8_BAR; PG8_SCHED;
;             PG8_LDB(B1, 1, 1); PG8_STAGE(PG8_SB(1, 0), b3, voffB);
;             PG8_BAR; PG8_WAIT_L(0); PG8_MMA(0, 1, At, B1); PG8_BAR;
	s_setprio 1
	v_mfma_f32_16x16x32_bf16 v[34:37], v[144:147], v[204:207], v[34:37]
	v_mfma_f32_16x16x32_bf16 v[26:29], v[176:179], v[204:207], v[26:29]
	v_mfma_f32_16x16x32_bf16 v[18:21], v[144:147], v[212:215], v[18:21]
	v_mfma_f32_16x16x32_bf16 v[10:13], v[176:179], v[212:215], v[10:13]
	v_mfma_f32_16x16x32_bf16 v[62:65], v[172:175], v[188:191], v[62:65]
	v_mfma_f32_16x16x32_bf16 v[58:61], v[180:183], v[188:191], v[58:61]
	v_mfma_f32_16x16x32_bf16 v[50:53], v[172:175], v[200:203], v[50:53]
	v_mfma_f32_16x16x32_bf16 v[42:45], v[180:183], v[200:203], v[42:45]
	v_mfma_f32_16x16x32_bf16 v[34:37], v[172:175], v[208:211], v[34:37]
	v_mfma_f32_16x16x32_bf16 v[26:29], v[180:183], v[208:211], v[26:29]
	v_mfma_f32_16x16x32_bf16 v[18:21], v[172:175], v[222:225], v[18:21]
	v_mfma_f32_16x16x32_bf16 v[10:13], v[180:183], v[222:225], v[10:13]
	v_mfma_f32_16x16x32_bf16 v[54:57], v[226:229], v[184:187], v[54:57]
	v_mfma_f32_16x16x32_bf16 v[46:49], v[234:237], v[184:187], v[46:49]
	v_mfma_f32_16x16x32_bf16 v[38:41], v[226:229], v[196:199], v[38:41]
	v_mfma_f32_16x16x32_bf16 v[30:33], v[234:237], v[196:199], v[30:33]
	v_mfma_f32_16x16x32_bf16 v[22:25], v[226:229], v[204:207], v[22:25]
	v_mfma_f32_16x16x32_bf16 v[14:17], v[234:237], v[204:207], v[14:17]
	v_mfma_f32_16x16x32_bf16 v[6:9], v[226:229], v[212:215], v[6:9]
	v_mfma_f32_16x16x32_bf16 v[2:5], v[234:237], v[212:215], v[2:5]
	v_mfma_f32_16x16x32_bf16 v[54:57], v[230:233], v[188:191], v[54:57]
	v_mfma_f32_16x16x32_bf16 v[46:49], v[238:241], v[188:191], v[46:49]
	v_mfma_f32_16x16x32_bf16 v[38:41], v[230:233], v[200:203], v[38:41]
	v_mfma_f32_16x16x32_bf16 v[30:33], v[238:241], v[200:203], v[30:33]
	v_mfma_f32_16x16x32_bf16 v[22:25], v[230:233], v[208:211], v[22:25]
	v_mfma_f32_16x16x32_bf16 v[14:17], v[238:241], v[208:211], v[14:17]
	v_mfma_f32_16x16x32_bf16 v[6:9], v[230:233], v[222:225], v[6:9]
	v_mfma_f32_16x16x32_bf16 v[2:5], v[238:241], v[222:225], v[2:5]
	s_setprio 0
	s_barrier
	s_add_i32 s8, 0, 0x18000
	v_add_u32_e32 v180, s8, v152
	ds_read_b128 v[144:147], v180
	ds_read_b128 v[172:175], v180 offset:1024
	ds_read_b128 v[176:179], v180 offset:2048
	ds_read_b128 v[180:183], v180 offset:3072
	s_add_u32 s94, s94, s4
	s_addc_u32 s95, s95, s5
	s_mov_b32 m0, s52
	v_lshl_add_u64 v[226:227], s[94:95], 0, v[130:131]
	ds_read_b128 v[184:187], v171 offset:32768
	ds_read_b128 v[188:191], v171 offset:33792
	ds_read_b128 v[196:199], v171 offset:34816
	ds_read_b128 v[200:203], v171 offset:35840
	ds_read_b128 v[204:207], v171 offset:36864
	ds_read_b128 v[208:211], v171 offset:37888
	ds_read_b128 v[212:215], v171 offset:38912
	ds_read_b128 v[222:225], v171 offset:39936
	global_load_lds_dwordx4 v[226:227], off
	v_lshl_add_u64 v[226:227], s[94:95], 0, v[134:135]
	s_mov_b32 m0, s53
	s_nop 0
	global_load_lds_dwordx4 v[226:227], off
	s_add_i32 s9, 0, 0x1c000
	v_add_u32_e32 v218, s9, v152
	ds_read_b128 v[226:229], v218
	ds_read_b128 v[230:233], v218 offset:1024
	ds_read_b128 v[234:237], v218 offset:2048
	ds_read_b128 v[238:241], v218 offset:3072
	s_waitcnt vmcnt(8)
	s_waitcnt lgkmcnt(0)
	v_mfma_f32_16x16x32_bf16 v[126:129], v[144:147], v[184:187], v[126:129]
	v_mfma_f32_16x16x32_bf16 v[122:125], v[176:179], v[184:187], v[122:125]
	v_mfma_f32_16x16x32_bf16 v[110:113], v[144:147], v[196:199], v[110:113]
	v_mfma_f32_16x16x32_bf16 v[106:109], v[176:179], v[196:199], v[106:109]
	s_barrier
	s_setprio 1
	v_mfma_f32_16x16x32_bf16 v[94:97], v[144:147], v[204:207], v[94:97]
	v_mfma_f32_16x16x32_bf16 v[90:93], v[176:179], v[204:207], v[90:93]
	v_mfma_f32_16x16x32_bf16 v[78:81], v[144:147], v[212:215], v[78:81]
	v_mfma_f32_16x16x32_bf16 v[74:77], v[176:179], v[212:215], v[74:77]
	v_mfma_f32_16x16x32_bf16 v[126:129], v[172:175], v[188:191], v[126:129]
	v_mfma_f32_16x16x32_bf16 v[122:125], v[180:183], v[188:191], v[122:125]
	v_mfma_f32_16x16x32_bf16 v[110:113], v[172:175], v[200:203], v[110:113]
	v_mfma_f32_16x16x32_bf16 v[106:109], v[180:183], v[200:203], v[106:109]
	v_mfma_f32_16x16x32_bf16 v[94:97], v[172:175], v[208:211], v[94:97]
	v_mfma_f32_16x16x32_bf16 v[90:93], v[180:183], v[208:211], v[90:93]
	v_mfma_f32_16x16x32_bf16 v[78:81], v[172:175], v[222:225], v[78:81]
	v_mfma_f32_16x16x32_bf16 v[74:77], v[180:183], v[222:225], v[74:77]
	v_mfma_f32_16x16x32_bf16 v[118:121], v[226:229], v[184:187], v[118:121]
	v_mfma_f32_16x16x32_bf16 v[114:117], v[234:237], v[184:187], v[114:117]
	v_mfma_f32_16x16x32_bf16 v[102:105], v[226:229], v[196:199], v[102:105]
	v_mfma_f32_16x16x32_bf16 v[98:101], v[234:237], v[196:199], v[98:101]
	v_mfma_f32_16x16x32_bf16 v[86:89], v[226:229], v[204:207], v[86:89]
	v_mfma_f32_16x16x32_bf16 v[82:85], v[234:237], v[204:207], v[82:85]
	v_mfma_f32_16x16x32_bf16 v[70:73], v[226:229], v[212:215], v[70:73]
	v_mfma_f32_16x16x32_bf16 v[66:69], v[234:237], v[212:215], v[66:69]
	v_mfma_f32_16x16x32_bf16 v[118:121], v[230:233], v[188:191], v[118:121]
	v_mfma_f32_16x16x32_bf16 v[114:117], v[238:241], v[188:191], v[114:117]
	v_mfma_f32_16x16x32_bf16 v[102:105], v[230:233], v[200:203], v[102:105]
	v_mfma_f32_16x16x32_bf16 v[98:101], v[238:241], v[200:203], v[98:101]
	v_mfma_f32_16x16x32_bf16 v[86:89], v[230:233], v[208:211], v[86:89]
	v_mfma_f32_16x16x32_bf16 v[82:85], v[238:241], v[208:211], v[82:85]
	v_mfma_f32_16x16x32_bf16 v[70:73], v[230:233], v[222:225], v[70:73]
	v_mfma_f32_16x16x32_bf16 v[66:69], v[238:241], v[222:225], v[66:69]
	s_setprio 0
	s_barrier
; __device__ __forceinline__ float pre_get(const Pre& p, int ai, int m, int fr) { return __shfl(p.v[ai], m * 16 + fr); }
; __device__ __forceinline__ float rstd_pre(const float* ss, float v) { return ss ? rsqrtf(v * (1.0f / 2048.0f) + 1e-6f) : 1.0f; }
; #define PG8_STAGE(bufoff, gbase, voff) do { _Pragma("unroll") for (int _i = 0; _i < 2; ++_i) \
;         __builtin_amdgcn_global_load_lds((const unsigned*)((const char*)(gbase) + (voff)[_i]), (LAS unsigned*)(lds + (bufoff) + ldsw + _i * 8192), 16, 0, 0); } while (0)
; #define PG8_LDA(dst, b, h) do { _Pragma("unroll") for (int m = 0; m < 4; ++m) _Pragma("unroll") for (int k = 0; k < 2; ++k) dst[m][k] = *(const LAS bf16x8*)(lds + PG8_SA(b, h) + aoff + m * 2048 + k * 1024); } while (0)
; #define PG8_WAIT_V(n) asm volatile("s_waitcnt vmcnt(" #n ")" ::: "memory")
; #define PG8_WAIT_L(n) asm volatile("s_waitcnt lgkmcnt(" #n ")" ::: "memory")
; template <class Epi>
; __device__ __forceinline__ void gemm_phase(LAS unsigned char* lds, const Gemm g, const Sched& S, const Epi& E) {
;     ...
;             PG8_LDA(At, 1, 1); PG8_STAGE(PG8_SA(1, 0), a3, voffA);
;             PG8_BAR; PG8_WAIT_L(0); PG8_MMA(1, 0, At, B0); PG8_BAR; PG8_SCHED;
;             PG8_STAGE(PG8_SB(1, 1), b3 + hstepB, voffB);
;             PG8_WAIT_V(6); PG8_BAR; PG8_MMA(1, 1, At, B1); PG8_BAR;
;         }
;     __device__ __forceinline__ void operator()(const Acc& acc, const Unit& u, int wr, int wc, int fr, int fq, const Pre& pre) const {
;         const int row0 = u.pm * 256 + wr * 64 + fr, col0 = wc * 32 + 8 * fq;
;         bf16_t* Oz = O + (size_t)(u.zb * sOb + u.zh * sOh);
;         float rs[2][4];
; #pragma unroll
;         for (int ai = 0; ai < 2; ++ai)
; #pragma unroll
;             for (int m = 0; m < 4; ++m) rs[ai][m] = rstd_pre(ss, pre_get(pre, ai, m, fr));
; #pragma unroll
;         for (int ai = 0; ai < 2; ++ai)
; #pragma unroll
;             for (int m = 0; m < 4; ++m) { float mx = -INFINITY;
; #pragma unroll
;                 for (int bj = 0; bj < 2; ++bj)
; #pragma unroll
;                     for (int n = 0; n < 2; ++n) { const f32x4 a = acc[ai][bj][m][n]; mx = fmaxf(mx, fmaxf(fmaxf(a[0], a[1]), fmaxf(a[2], a[3]))); }
;                 mx *= rs[ai][m];
;                 mx = fmaxf(mx, __shfl_xor(mx, 16)); mx = fmaxf(mx, __shfl_xor(mx, 32));
;                 if (fq == 0) X[(ai * 128 + wr * 64 + m * 16 + fr) * 4 + wc] = mx; }
	s_add_i32 s8, s8, s39
	v_lshl_add_u64 v[148:149], v[148:149], 0, s[60:61]
	s_mov_b32 m0, s8
	s_nop 0
	global_load_lds_dwordx4 v[148:149], off
	v_lshl_add_u64 v[148:149], v[192:193], 0, s[60:61]
	s_add_i32 m0, s8, 0x2000
	s_nop 0
	global_load_lds_dwordx4 v[148:149], off
	s_mov_b32 m0, s67
	v_lshl_add_u64 v[148:149], v[194:195], 0, s[60:61]
	ds_read_b128 v[184:187], v171 offset:49152
	ds_read_b128 v[188:191], v171 offset:50176
	ds_read_b128 v[196:199], v171 offset:51200
	ds_read_b128 v[200:203], v171 offset:52224
	ds_read_b128 v[204:207], v171 offset:53248
	ds_read_b128 v[208:211], v171 offset:54272
	ds_read_b128 v[212:215], v171 offset:55296
	ds_read_b128 v[222:225], v171 offset:56320
	global_load_lds_dwordx4 v[148:149], off
	v_lshl_add_u64 v[148:149], v[216:217], 0, s[60:61]
	s_mov_b32 m0, s2
	s_nop 0
	global_load_lds_dwordx4 v[148:149], off
	s_add_i32 s8, s9, s39
	v_lshl_add_u64 v[148:149], v[242:243], 0, s[60:61]
	s_mov_b32 m0, s8
	s_nop 0
	global_load_lds_dwordx4 v[148:149], off
	v_lshl_add_u64 v[148:149], v[244:245], 0, s[60:61]
	s_add_i32 m0, s8, 0x2000
	s_nop 0
	global_load_lds_dwordx4 v[148:149], off
	s_waitcnt vmcnt(8)
	s_waitcnt lgkmcnt(0)
	v_mfma_f32_16x16x32_bf16 v[62:65], v[144:147], v[184:187], v[62:65]
	v_mfma_f32_16x16x32_bf16 v[58:61], v[176:179], v[184:187], v[58:61]
	v_mfma_f32_16x16x32_bf16 v[50:53], v[144:147], v[196:199], v[50:53]
	v_mfma_f32_16x16x32_bf16 v[42:45], v[176:179], v[196:199], v[42:45]
	s_barrier
	s_setprio 1
	v_mfma_f32_16x16x32_bf16 v[34:37], v[144:147], v[204:207], v[34:37]
	v_mfma_f32_16x16x32_bf16 v[26:29], v[176:179], v[204:207], v[26:29]
	v_mfma_f32_16x16x32_bf16 v[18:21], v[144:147], v[212:215], v[18:21]
	v_mfma_f32_16x16x32_bf16 v[10:13], v[176:179], v[212:215], v[10:13]
	v_mfma_f32_16x16x32_bf16 v[62:65], v[172:175], v[188:191], v[62:65]
	v_mfma_f32_16x16x32_bf16 v[58:61], v[180:183], v[188:191], v[58:61]
	v_mfma_f32_16x16x32_bf16 v[50:53], v[172:175], v[200:203], v[50:53]
	v_mfma_f32_16x16x32_bf16 v[42:45], v[180:183], v[200:203], v[42:45]
	v_mfma_f32_16x16x32_bf16 v[34:37], v[172:175], v[208:211], v[34:37]
	v_mfma_f32_16x16x32_bf16 v[26:29], v[180:183], v[208:211], v[26:29]
	v_mfma_f32_16x16x32_bf16 v[18:21], v[172:175], v[222:225], v[18:21]
	v_mfma_f32_16x16x32_bf16 v[10:13], v[180:183], v[222:225], v[10:13]
	v_mfma_f32_16x16x32_bf16 v[54:57], v[226:229], v[184:187], v[54:57]
	v_mfma_f32_16x16x32_bf16 v[46:49], v[234:237], v[184:187], v[46:49]
	v_mfma_f32_16x16x32_bf16 v[38:41], v[226:229], v[196:199], v[38:41]
	v_mfma_f32_16x16x32_bf16 v[30:33], v[234:237], v[196:199], v[30:33]
	v_mfma_f32_16x16x32_bf16 v[22:25], v[226:229], v[204:207], v[22:25]
	v_mfma_f32_16x16x32_bf16 v[14:17], v[234:237], v[204:207], v[14:17]
	v_mfma_f32_16x16x32_bf16 v[6:9], v[226:229], v[212:215], v[6:9]
	v_mfma_f32_16x16x32_bf16 v[2:5], v[234:237], v[212:215], v[2:5]
	v_mfma_f32_16x16x32_bf16 v[54:57], v[230:233], v[188:191], v[54:57]
	v_mfma_f32_16x16x32_bf16 v[46:49], v[238:241], v[188:191], v[46:49]
	v_mfma_f32_16x16x32_bf16 v[38:41], v[230:233], v[200:203], v[38:41]
	v_mfma_f32_16x16x32_bf16 v[30:33], v[238:241], v[200:203], v[30:33]
	v_mfma_f32_16x16x32_bf16 v[22:25], v[230:233], v[208:211], v[22:25]
	v_mfma_f32_16x16x32_bf16 v[14:17], v[238:241], v[208:211], v[14:17]
	v_mfma_f32_16x16x32_bf16 v[6:9], v[230:233], v[222:225], v[6:9]
	v_mfma_f32_16x16x32_bf16 v[2:5], v[238:241], v[222:225], v[2:5]
	s_setprio 0
	s_add_u32 s92, s92, 0x100
	s_addc_u32 s93, s93, 0
	s_add_u32 s34, s34, 0x100
	s_addc_u32 s35, s35, 0
	s_cmp_ge_u32 s14, s73
	s_mov_b32 s66, s14
	s_barrier
	s_cbranch_scc0 .LBB0_400
	v_and_b32_e32 v144, 64, v220
	v_or_b32_e32 v144, v144, v150
	v_lshlrev_b32_e32 v172, 2, v144
	ds_bpermute_b32 v145, v172, v143
	ds_bpermute_b32 v144, v172, v143 offset:64
	s_mov_b32 s8, 0x3a000000
	v_mov_b32_e32 v232, 0x358637bd
	s_mov_b32 s97, 0x800000
	ds_bpermute_b32 v147, v172, v143 offset:128
	s_waitcnt lgkmcnt(0)
	v_pk_fma_f32 v[148:149], v[144:145], s[8:9], v[232:233] op_sel_hi:[1,0,0]
	ds_bpermute_b32 v146, v172, v143 offset:192
	v_mul_f32_e32 v143, 0x4b800000, v149
	v_cmp_gt_f32_e32 vcc, s97, v149
	v_max_f32_e32 v174, v128, v128
	v_max_f32_e32 v175, v124, v124
	v_cndmask_b32_e32 v143, v149, v143, vcc
	v_rsq_f32_e32 v149, v143
	v_max_f32_e32 v176, v116, v116
	ds_bpermute_b32 v145, v172, v142
	ds_bpermute_b32 v144, v172, v142 offset:64
	v_mul_f32_e32 v173, 0x45800000, v149
	v_cndmask_b32_e32 v149, v149, v173, vcc
	v_max_f32_e32 v173, v129, v129
	v_max_f32_e32 v173, v174, v173
	v_max_f32_e32 v174, v125, v125
	v_max_f32_e32 v174, v175, v174
	v_max3_f32 v173, v126, v127, v173
	v_max3_f32 v174, v122, v123, v174
	v_max3_f32 v173, v173, s72, v174
	v_max_f32_e32 v174, v121, v121
	v_max_f32_e32 v175, v120, v120
	v_max_f32_e32 v174, v175, v174
	v_max_f32_e32 v175, v117, v117
	v_max_f32_e32 v175, v176, v175
	v_cmp_lt_i32_e32 vcc, v221, v247
	v_max3_f32 v174, v118, v119, v174
	v_max3_f32 v175, v114, v115, v175
	v_cndmask_b32_e64 v177, v149, 1.0, s[80:81]
	v_cndmask_b32_e32 v149, v220, v221, vcc
	v_max3_f32 v173, v173, v174, v175
	v_lshlrev_b32_e32 v149, 2, v149
	v_mul_f32_e32 v173, v173, v177
	ds_bpermute_b32 v174, v149, v173
	v_cmp_lt_i32_e32 vcc, v248, v247
	ds_bpermute_b32 v143, v172, v142 offset:128
	ds_bpermute_b32 v142, v172, v142 offset:192
	v_cndmask_b32_e32 v172, v220, v248, vcc
	s_waitcnt lgkmcnt(0)
	v_max_f32_e32 v174, v174, v174
	v_lshlrev_b32_e32 v172, 2, v172
	v_max_f32_e32 v173, v173, v174
	ds_bpermute_b32 v174, v172, v173
	v_cmp_gt_f32_e32 vcc, s97, v148
	v_add_u32_e32 v178, s51, v154
	v_readfirstlane_b32 s98, v219
	s_nop 1
	s_bitcmp1_b32 s98, 8
	s_cbranch_scc1 .Lresync_x_400_p
	s_barrier
	s_branch .Lresync_x_400

; #define PG8_STAGE(bufoff, gbase, voff) do { _Pragma("unroll") for (int _i = 0; _i < 2; ++_i) \
;         __builtin_amdgcn_global_load_lds((const unsigned*)((const char*)(gbase) + (voff)[_i]), (LAS unsigned*)(lds + (bufoff) + ldsw + _i * 8192), 16, 0, 0); } while (0)
; #define PG8_LDA(dst, b, h) do { _Pragma("unroll") for (int m = 0; m < 4; ++m) _Pragma("unroll") for (int k = 0; k < 2; ++k) dst[m][k] = *(const LAS bf16x8*)(lds + PG8_SA(b, h) + aoff + m * 2048 + k * 1024); } while (0)
; #define PG8_LDB(dst, b, h) do { _Pragma("unroll") for (int n = 0; n < 2; ++n) _Pragma("unroll") for (int k = 0; k < 2; ++k) dst[n][k] = *(const LAS bf16x8*)(lds + PG8_SB(b, h) + boff + n * 2048 + k * 1024); } while (0)
; #define PG8_MMA(ai, bj, At, Bt) do { __builtin_amdgcn_s_setprio(1); _Pragma("unroll") for (int m = 0; m < 4; ++m) _Pragma("unroll") for (int n = 0; n < 2; ++n) _Pragma("unroll") for (int k = 0; k < 2; ++k) \
;         acc[ai][bj][m][n] = __builtin_amdgcn_mfma_f32_16x16x32_bf16(Bt[n][k], At[m][k], acc[ai][bj][m][n], 0, 0, 0); __builtin_amdgcn_s_setprio(0); } while (0)
; #define PG8_WAIT_V(n) asm volatile("s_waitcnt vmcnt(" #n ")" ::: "memory")
; #define PG8_WAIT_L(n) asm volatile("s_waitcnt lgkmcnt(" #n ")" ::: "memory")
; template <class Epi>
; __device__ __forceinline__ void gemm_phase(LAS unsigned char* lds, const Gemm g, const Sched& S, const Epi& E) {
;     ...
;         for (int t = 0; t < nt; t += 2) {
;             const bool last = (t == nt - 2);
;             const char* a1 = cA + (size_t)(t + 1) * kstep;
;             const char* a2 = last ? nA : cA + (size_t)(t + 2) * kstep; const char* b2 = last ? nB : cB + (size_t)(t + 2) * kstep;
;             const char* a3 = a2 + kstep; const char* b3 = b2 + kstep;
;             PG8_LDB(B0, 0, 0); PG8_SCHED; PG8_LDA(At, 0, 0); PG8_STAGE(PG8_SA(1, 1), a1 + hstepA, voffA);
;             PG8_WAIT_L(8); PG8_BAR; PG8_WAIT_L(0); PG8_MMA(0, 0, At, B0); PG8_BAR; PG8_SCHED;
;             PG8_LDB(B1, 0, 1); PG8_STAGE(PG8_SB(0, 0), b2, voffB);
;             PG8_BAR; PG8_WAIT_L(0); PG8_MMA(0, 1, At, B1); PG8_BAR;
;             PG8_LDA(At, 0, 1); PG8_STAGE(PG8_SA(0, 0), a2, voffA);
;             PG8_BAR; PG8_WAIT_L(0); PG8_MMA(1, 0, At, B0); PG8_BAR; PG8_SCHED;
;             PG8_STAGE(PG8_SB(0, 1), b2 + hstepB, voffB);
;             PG8_WAIT_V(6); PG8_BAR; PG8_MMA(1, 1, At, B1); PG8_BAR;
.Lresync_y_461:
.LBB0_461:
	s_add_i32 s14, s88, 2
	s_add_u32 s8, s4, 0x80
	s_addc_u32 s9, s5, 0
	s_add_i32 s15, 0, 0x10000
	v_add_u32_e32 v114, s15, v211
	ds_read_b128 v[82:85], v114
	ds_read_b128 v[94:97], v114 offset:1024
	ds_read_b128 v[98:101], v114 offset:2048
	ds_read_b128 v[114:117], v114 offset:3072
	s_cmp_eq_u32 s42, s88
	s_cselect_b32 s88, s57, s8
	s_cselect_b32 s89, s71, s9
	s_cselect_b32 s91, s59, s35
	s_cselect_b32 s90, s72, s34
	v_lshl_add_u64 v[178:179], s[4:5], 0, v[202:203]
	s_add_i32 m0, s24, 0xc000
	ds_read_b128 v[122:125], v213
	ds_read_b128 v[130:133], v213 offset:1024
	ds_read_b128 v[146:149], v213 offset:2048
	ds_read_b128 v[150:153], v213 offset:3072
	ds_read_b128 v[162:165], v213 offset:4096
	ds_read_b128 v[166:169], v213 offset:5120
	ds_read_b128 v[170:173], v213 offset:6144
	ds_read_b128 v[174:177], v213 offset:7168
	global_load_lds_dwordx4 v[178:179], off
	v_lshl_add_u64 v[178:179], s[4:5], 0, v[204:205]
	s_add_i32 m0, s24, 0xe000
	s_nop 0
	global_load_lds_dwordx4 v[178:179], off
	s_add_i32 s8, 0, 0x14000
	v_add_u32_e32 v190, s8, v211
	ds_read_b128 v[178:181], v190
	ds_read_b128 v[182:185], v190 offset:1024
	ds_read_b128 v[186:189], v190 offset:2048
	ds_read_b128 v[190:193], v190 offset:3072
	s_waitcnt vmcnt(8)
	s_waitcnt lgkmcnt(0)
	v_mfma_f32_16x16x32_bf16 v[158:161], v[82:85], v[122:125], v[158:161]
	v_mfma_f32_16x16x32_bf16 v[154:157], v[98:101], v[122:125], v[154:157]
	v_mfma_f32_16x16x32_bf16 v[134:137], v[82:85], v[146:149], v[134:137]
	v_mfma_f32_16x16x32_bf16 v[126:129], v[98:101], v[146:149], v[126:129]
	s_barrier
	s_setprio 1
	v_mfma_f32_16x16x32_bf16 v[106:109], v[82:85], v[162:165], v[106:109]
	v_mfma_f32_16x16x32_bf16 v[102:105], v[98:101], v[162:165], v[102:105]
	v_mfma_f32_16x16x32_bf16 v[78:81], v[82:85], v[170:173], v[78:81]
	v_mfma_f32_16x16x32_bf16 v[74:77], v[98:101], v[170:173], v[74:77]
	v_mfma_f32_16x16x32_bf16 v[158:161], v[94:97], v[130:133], v[158:161]
	v_mfma_f32_16x16x32_bf16 v[154:157], v[114:117], v[130:133], v[154:157]
	v_mfma_f32_16x16x32_bf16 v[134:137], v[94:97], v[150:153], v[134:137]
	v_mfma_f32_16x16x32_bf16 v[126:129], v[114:117], v[150:153], v[126:129]
	v_mfma_f32_16x16x32_bf16 v[106:109], v[94:97], v[166:169], v[106:109]
	v_mfma_f32_16x16x32_bf16 v[102:105], v[114:117], v[166:169], v[102:105]
	v_mfma_f32_16x16x32_bf16 v[78:81], v[94:97], v[174:177], v[78:81]
	v_mfma_f32_16x16x32_bf16 v[74:77], v[114:117], v[174:177], v[74:77]
	v_mfma_f32_16x16x32_bf16 v[142:145], v[178:181], v[122:125], v[142:145]
	v_mfma_f32_16x16x32_bf16 v[118:121], v[178:181], v[146:149], v[118:121]
	v_mfma_f32_16x16x32_bf16 v[110:113], v[186:189], v[146:149], v[110:113]
	v_mfma_f32_16x16x32_bf16 v[90:93], v[178:181], v[162:165], v[90:93]
	v_mfma_f32_16x16x32_bf16 v[86:89], v[186:189], v[162:165], v[86:89]
	v_mfma_f32_16x16x32_bf16 v[70:73], v[178:181], v[170:173], v[70:73]
	v_mfma_f32_16x16x32_bf16 v[66:69], v[186:189], v[170:173], v[66:69]
	v_mfma_f32_16x16x32_bf16 v[142:145], v[182:185], v[130:133], v[142:145]
	v_mfma_f32_16x16x32_bf16 v[122:125], v[186:189], v[122:125], v[138:141]
	v_mfma_f32_16x16x32_bf16 v[118:121], v[182:185], v[150:153], v[118:121]
	v_mfma_f32_16x16x32_bf16 v[110:113], v[190:193], v[150:153], v[110:113]
	v_mfma_f32_16x16x32_bf16 v[90:93], v[182:185], v[166:169], v[90:93]
	v_mfma_f32_16x16x32_bf16 v[86:89], v[190:193], v[166:169], v[86:89]
	v_mfma_f32_16x16x32_bf16 v[70:73], v[182:185], v[174:177], v[70:73]
	v_mfma_f32_16x16x32_bf16 v[66:69], v[190:193], v[174:177], v[66:69]
	v_mfma_f32_16x16x32_bf16 v[122:125], v[190:193], v[130:133], v[122:125]
	s_setprio 0
	s_barrier
	s_add_i32 s9, s15, s3
	v_lshl_add_u64 v[194:195], s[90:91], 0, v[0:1]
	s_mov_b32 m0, s9
	s_nop 0
	global_load_lds_dwordx4 v[194:195], off
	v_lshl_add_u64 v[206:207], s[90:91], 0, v[200:201]
	s_add_i32 m0, s9, 0x2000
	s_nop 0
	global_load_lds_dwordx4 v[206:207], off
	s_mov_b32 m0, s24
	v_lshl_add_u64 v[208:209], s[88:89], 0, v[196:197]
	ds_read_b128 v[130:133], v213 offset:16384
	ds_read_b128 v[138:141], v213 offset:17408
	ds_read_b128 v[146:149], v213 offset:18432
	ds_read_b128 v[150:153], v213 offset:19456
	ds_read_b128 v[162:165], v213 offset:20480
	ds_read_b128 v[166:169], v213 offset:21504
	ds_read_b128 v[170:173], v213 offset:22528
	ds_read_b128 v[174:177], v213 offset:23552
	global_load_lds_dwordx4 v[208:209], off
	v_lshl_add_u64 v[214:215], s[88:89], 0, v[198:199]
	s_mov_b32 m0, s33
	s_nop 0
	global_load_lds_dwordx4 v[214:215], off
	s_add_u32 s90, s90, s78
	s_addc_u32 s91, s91, s79
	s_add_i32 s8, s8, s3
	v_lshl_add_u64 v[216:217], s[90:91], 0, v[0:1]
	s_mov_b32 m0, s8
	v_lshl_add_u64 v[222:223], s[90:91], 0, v[200:201]
	global_load_lds_dwordx4 v[216:217], off
	s_add_i32 m0, s8, 0x2000
	s_nop 0
	global_load_lds_dwordx4 v[222:223], off
	s_waitcnt vmcnt(8)
	s_waitcnt lgkmcnt(0)
	v_mfma_f32_16x16x32_bf16 v[62:65], v[82:85], v[130:133], v[62:65]
	v_mfma_f32_16x16x32_bf16 v[58:61], v[98:101], v[130:133], v[58:61]
	v_mfma_f32_16x16x32_bf16 v[46:49], v[82:85], v[146:149], v[46:49]
	v_mfma_f32_16x16x32_bf16 v[42:45], v[98:101], v[146:149], v[42:45]
	s_barrier
; #define PG8_STAGE(bufoff, gbase, voff) do { _Pragma("unroll") for (int _i = 0; _i < 2; ++_i) \
;         __builtin_amdgcn_global_load_lds((const unsigned*)((const char*)(gbase) + (voff)[_i]), (LAS unsigned*)(lds + (bufoff) + ldsw + _i * 8192), 16, 0, 0); } while (0)
; #define PG8_LDA(dst, b, h) do { _Pragma("unroll") for (int m = 0; m < 4; ++m) _Pragma("unroll") for (int k = 0; k < 2; ++k) dst[m][k] = *(const LAS bf16x8*)(lds + PG8_SA(b, h) + aoff + m * 2048 + k * 1024); } while (0)
; #define PG8_LDB(dst, b, h) do { _Pragma("unroll") for (int n = 0; n < 2; ++n) _Pragma("unroll") for (int k = 0; k < 2; ++k) dst[n][k] = *(const LAS bf16x8*)(lds + PG8_SB(b, h) + boff + n * 2048 + k * 1024); } while (0)
; #define PG8_MMA(ai, bj, At, Bt) do { __builtin_amdgcn_s_setprio(1); _Pragma("unroll") for (int m = 0; m < 4; ++m) _Pragma("unroll") for (int n = 0; n < 2; ++n) _Pragma("unroll") for (int k = 0; k < 2; ++k) \
;         acc[ai][bj][m][n] = __builtin_amdgcn_mfma_f32_16x16x32_bf16(Bt[n][k], At[m][k], acc[ai][bj][m][n], 0, 0, 0); __builtin_amdgcn_s_setprio(0); } while (0)
; #define PG8_WAIT_V(n) asm volatile("s_waitcnt vmcnt(" #n ")" ::: "memory")
; #define PG8_WAIT_L(n) asm volatile("s_waitcnt lgkmcnt(" #n ")" ::: "memory")
; #define PG8_BAR __builtin_amdgcn_s_barrier()
; #define PG8_SCHED __builtin_amdgcn_sched_barrier(0)
; template <class Epi>
; __device__ __forceinline__ void gemm_phase(LAS unsigned char* lds, const Gemm g, const Sched& S, const Epi& E) {
;     ...
;             PG8_WAIT_V(6); PG8_BAR; PG8_MMA(1, 1, At, B1); PG8_BAR;
;             PG8_LDB(B0, 1, 0); PG8_SCHED; PG8_LDA(At, 1, 0); PG8_STAGE(PG8_SA(0, 1), a2 + hstepA, voffA);
;             PG8_WAIT_L(8); PG8_BAR; PG8_WAIT_L(0); PG8_MMA(0, 0, At, B0); PG8_BAR; PG8_SCHED;
;             PG8_LDB(B1, 1, 1); PG8_STAGE(PG8_SB(1, 0), b3, voffB);
;             PG8_BAR; PG8_WAIT_L(0); PG8_MMA(0, 1, At, B1); PG8_BAR;
	s_setprio 1
	v_mfma_f32_16x16x32_bf16 v[30:33], v[82:85], v[162:165], v[30:33]
	v_mfma_f32_16x16x32_bf16 v[26:29], v[98:101], v[162:165], v[26:29]
	v_mfma_f32_16x16x32_bf16 v[14:17], v[82:85], v[170:173], v[14:17]
	v_mfma_f32_16x16x32_bf16 v[10:13], v[98:101], v[170:173], v[10:13]
	v_mfma_f32_16x16x32_bf16 v[62:65], v[94:97], v[138:141], v[62:65]
	v_mfma_f32_16x16x32_bf16 v[58:61], v[114:117], v[138:141], v[58:61]
	v_mfma_f32_16x16x32_bf16 v[46:49], v[94:97], v[150:153], v[46:49]
	v_mfma_f32_16x16x32_bf16 v[42:45], v[114:117], v[150:153], v[42:45]
	v_mfma_f32_16x16x32_bf16 v[30:33], v[94:97], v[166:169], v[30:33]
	v_mfma_f32_16x16x32_bf16 v[26:29], v[114:117], v[166:169], v[26:29]
	v_mfma_f32_16x16x32_bf16 v[14:17], v[94:97], v[174:177], v[14:17]
	v_mfma_f32_16x16x32_bf16 v[10:13], v[114:117], v[174:177], v[10:13]
	v_mfma_f32_16x16x32_bf16 v[54:57], v[178:181], v[130:133], v[54:57]
	v_mfma_f32_16x16x32_bf16 v[50:53], v[186:189], v[130:133], v[50:53]
	v_mfma_f32_16x16x32_bf16 v[38:41], v[178:181], v[146:149], v[38:41]
	v_mfma_f32_16x16x32_bf16 v[34:37], v[186:189], v[146:149], v[34:37]
	v_mfma_f32_16x16x32_bf16 v[22:25], v[178:181], v[162:165], v[22:25]
	v_mfma_f32_16x16x32_bf16 v[18:21], v[186:189], v[162:165], v[18:21]
	v_mfma_f32_16x16x32_bf16 v[6:9], v[178:181], v[170:173], v[6:9]
	v_mfma_f32_16x16x32_bf16 v[2:5], v[186:189], v[170:173], v[2:5]
	v_mfma_f32_16x16x32_bf16 v[54:57], v[182:185], v[138:141], v[54:57]
	v_mfma_f32_16x16x32_bf16 v[50:53], v[190:193], v[138:141], v[50:53]
	v_mfma_f32_16x16x32_bf16 v[38:41], v[182:185], v[150:153], v[38:41]
	v_mfma_f32_16x16x32_bf16 v[34:37], v[190:193], v[150:153], v[34:37]
	v_mfma_f32_16x16x32_bf16 v[22:25], v[182:185], v[166:169], v[22:25]
	v_mfma_f32_16x16x32_bf16 v[18:21], v[190:193], v[166:169], v[18:21]
	v_mfma_f32_16x16x32_bf16 v[6:9], v[182:185], v[174:177], v[6:9]
	v_mfma_f32_16x16x32_bf16 v[2:5], v[190:193], v[174:177], v[2:5]
	s_setprio 0
	s_barrier
	s_add_i32 s8, 0, 0x18000
	v_add_u32_e32 v114, s8, v211
	ds_read_b128 v[82:85], v114
	ds_read_b128 v[94:97], v114 offset:1024
	ds_read_b128 v[98:101], v114 offset:2048
	ds_read_b128 v[114:117], v114 offset:3072
	s_add_u32 s88, s88, s36
	s_addc_u32 s89, s89, s37
	s_mov_b32 m0, s38
	v_lshl_add_u64 v[178:179], s[88:89], 0, v[196:197]
	ds_read_b128 v[130:133], v213 offset:32768
	ds_read_b128 v[138:141], v213 offset:33792
	ds_read_b128 v[146:149], v213 offset:34816
	ds_read_b128 v[150:153], v213 offset:35840
	ds_read_b128 v[162:165], v213 offset:36864
	ds_read_b128 v[166:169], v213 offset:37888
	ds_read_b128 v[170:173], v213 offset:38912
	ds_read_b128 v[174:177], v213 offset:39936
	global_load_lds_dwordx4 v[178:179], off
	v_lshl_add_u64 v[178:179], s[88:89], 0, v[198:199]
	s_mov_b32 m0, s39
	s_nop 0
	global_load_lds_dwordx4 v[178:179], off
	s_add_i32 s9, 0, 0x1c000
	v_add_u32_e32 v190, s9, v211
	ds_read_b128 v[178:181], v190
	ds_read_b128 v[182:185], v190 offset:1024
	ds_read_b128 v[186:189], v190 offset:2048
	ds_read_b128 v[190:193], v190 offset:3072
	s_waitcnt vmcnt(8)
	s_waitcnt lgkmcnt(0)
	v_mfma_f32_16x16x32_bf16 v[158:161], v[82:85], v[130:133], v[158:161]
	v_mfma_f32_16x16x32_bf16 v[154:157], v[98:101], v[130:133], v[154:157]
	v_mfma_f32_16x16x32_bf16 v[134:137], v[82:85], v[146:149], v[134:137]
	v_mfma_f32_16x16x32_bf16 v[126:129], v[98:101], v[146:149], v[126:129]
	s_barrier
	s_setprio 1
	v_mfma_f32_16x16x32_bf16 v[106:109], v[82:85], v[162:165], v[106:109]
	v_mfma_f32_16x16x32_bf16 v[102:105], v[98:101], v[162:165], v[102:105]
	v_mfma_f32_16x16x32_bf16 v[78:81], v[82:85], v[170:173], v[78:81]
	v_mfma_f32_16x16x32_bf16 v[74:77], v[98:101], v[170:173], v[74:77]
	v_mfma_f32_16x16x32_bf16 v[158:161], v[94:97], v[138:141], v[158:161]
	v_mfma_f32_16x16x32_bf16 v[154:157], v[114:117], v[138:141], v[154:157]
	v_mfma_f32_16x16x32_bf16 v[134:137], v[94:97], v[150:153], v[134:137]
	v_mfma_f32_16x16x32_bf16 v[126:129], v[114:117], v[150:153], v[126:129]
	v_mfma_f32_16x16x32_bf16 v[106:109], v[94:97], v[166:169], v[106:109]
	v_mfma_f32_16x16x32_bf16 v[102:105], v[114:117], v[166:169], v[102:105]
	v_mfma_f32_16x16x32_bf16 v[78:81], v[94:97], v[174:177], v[78:81]
	v_mfma_f32_16x16x32_bf16 v[74:77], v[114:117], v[174:177], v[74:77]
	v_mfma_f32_16x16x32_bf16 v[142:145], v[178:181], v[130:133], v[142:145]
	v_mfma_f32_16x16x32_bf16 v[122:125], v[186:189], v[130:133], v[122:125]
	v_mfma_f32_16x16x32_bf16 v[118:121], v[178:181], v[146:149], v[118:121]
	v_mfma_f32_16x16x32_bf16 v[110:113], v[186:189], v[146:149], v[110:113]
	v_mfma_f32_16x16x32_bf16 v[90:93], v[178:181], v[162:165], v[90:93]
	v_mfma_f32_16x16x32_bf16 v[86:89], v[186:189], v[162:165], v[86:89]
	v_mfma_f32_16x16x32_bf16 v[70:73], v[178:181], v[170:173], v[70:73]
	v_mfma_f32_16x16x32_bf16 v[66:69], v[186:189], v[170:173], v[66:69]
	v_mfma_f32_16x16x32_bf16 v[142:145], v[182:185], v[138:141], v[142:145]
	v_mfma_f32_16x16x32_bf16 v[138:141], v[190:193], v[138:141], v[122:125]
	v_mfma_f32_16x16x32_bf16 v[118:121], v[182:185], v[150:153], v[118:121]
	v_mfma_f32_16x16x32_bf16 v[110:113], v[190:193], v[150:153], v[110:113]
	v_mfma_f32_16x16x32_bf16 v[90:93], v[182:185], v[166:169], v[90:93]
	v_mfma_f32_16x16x32_bf16 v[86:89], v[190:193], v[166:169], v[86:89]
	v_mfma_f32_16x16x32_bf16 v[70:73], v[182:185], v[174:177], v[70:73]
	v_mfma_f32_16x16x32_bf16 v[66:69], v[190:193], v[174:177], v[66:69]
	s_setprio 0
	s_barrier
; #define PG8_STAGE(bufoff, gbase, voff) do { _Pragma("unroll") for (int _i = 0; _i < 2; ++_i) \
;         __builtin_amdgcn_global_load_lds((const unsigned*)((const char*)(gbase) + (voff)[_i]), (LAS unsigned*)(lds + (bufoff) + ldsw + _i * 8192), 16, 0, 0); } while (0)
; #define PG8_LDA(dst, b, h) do { _Pragma("unroll") for (int m = 0; m < 4; ++m) _Pragma("unroll") for (int k = 0; k < 2; ++k) dst[m][k] = *(const LAS bf16x8*)(lds + PG8_SA(b, h) + aoff + m * 2048 + k * 1024); } while (0)
; #define PG8_MMA(ai, bj, At, Bt) do { __builtin_amdgcn_s_setprio(1); _Pragma("unroll") for (int m = 0; m < 4; ++m) _Pragma("unroll") for (int n = 0; n < 2; ++n) _Pragma("unroll") for (int k = 0; k < 2; ++k) \
;         acc[ai][bj][m][n] = __builtin_amdgcn_mfma_f32_16x16x32_bf16(Bt[n][k], At[m][k], acc[ai][bj][m][n], 0, 0, 0); __builtin_amdgcn_s_setprio(0); } while (0)
; #define PG8_WAIT_V(n) asm volatile("s_waitcnt vmcnt(" #n ")" ::: "memory")
; #define PG8_WAIT_L(n) asm volatile("s_waitcnt lgkmcnt(" #n ")" ::: "memory")
; #define PG8_BAR __builtin_amdgcn_s_barrier()
; #define PG8_SCHED __builtin_amdgcn_sched_barrier(0)
; template <class Epi>
; __device__ __forceinline__ void gemm_phase(LAS unsigned char* lds, const Gemm g, const Sched& S, const Epi& E) {
;     ...
;             PG8_LDA(At, 1, 1); PG8_STAGE(PG8_SA(1, 0), a3, voffA);
;             PG8_BAR; PG8_WAIT_L(0); PG8_MMA(1, 0, At, B0); PG8_BAR; PG8_SCHED;
;             PG8_STAGE(PG8_SB(1, 1), b3 + hstepB, voffB);
;             PG8_WAIT_V(6); PG8_BAR; PG8_MMA(1, 1, At, B1); PG8_BAR;
;         }
;     __device__ __forceinline__ void operator()(const Acc& acc, const Unit& u, int wr, int wc, int fr, int fq, const Pre& pre) const {
;         const int row0 = u.pm * 256 + wr * 64 + fr, col0 = u.pn * 256 + wc * 32 + 8 * fq;
; #pragma unroll
;         for (int ai = 0; ai < 2; ++ai) {
;             u32x4 gw[4][2], pw[4][2];
; #pragma unroll
;             for (int m = 0; m < 4; ++m)
; #pragma unroll
;                 for (int bj = 0; bj < 2; ++bj) { const size_t off = (size_t)(row0 + ai * 128 + m * 16) * ldc + col0 + bj * 128;
;                     gw[m][bj] = *(const u32x4*)(gate + off); if (add) pw[m][bj] = *(const u32x4*)(O + off); }
	s_add_i32 s8, s8, s3
	v_lshl_add_u64 v[194:195], v[194:195], 0, s[60:61]
	s_mov_b32 m0, s8
	s_nop 0
	global_load_lds_dwordx4 v[194:195], off
	v_lshl_add_u64 v[194:195], v[206:207], 0, s[60:61]
	s_add_i32 m0, s8, 0x2000
	s_nop 0
	global_load_lds_dwordx4 v[194:195], off
	s_mov_b32 m0, s40
	v_lshl_add_u64 v[194:195], v[208:209], 0, s[60:61]
	ds_read_b128 v[122:125], v213 offset:49152
	ds_read_b128 v[130:133], v213 offset:50176
	ds_read_b128 v[146:149], v213 offset:51200
	ds_read_b128 v[150:153], v213 offset:52224
	ds_read_b128 v[162:165], v213 offset:53248
	ds_read_b128 v[166:169], v213 offset:54272
	ds_read_b128 v[170:173], v213 offset:55296
	ds_read_b128 v[174:177], v213 offset:56320
	global_load_lds_dwordx4 v[194:195], off
	v_lshl_add_u64 v[194:195], v[214:215], 0, s[60:61]
	s_mov_b32 m0, s41
	s_nop 0
	global_load_lds_dwordx4 v[194:195], off
	s_add_i32 s8, s9, s3
	v_lshl_add_u64 v[194:195], v[216:217], 0, s[60:61]
	s_mov_b32 m0, s8
	s_nop 0
	global_load_lds_dwordx4 v[194:195], off
	v_lshl_add_u64 v[194:195], v[222:223], 0, s[60:61]
	s_add_i32 m0, s8, 0x2000
	s_nop 0
	global_load_lds_dwordx4 v[194:195], off
	s_waitcnt vmcnt(8)
	s_waitcnt lgkmcnt(0)
	v_mfma_f32_16x16x32_bf16 v[62:65], v[82:85], v[122:125], v[62:65]
	v_mfma_f32_16x16x32_bf16 v[58:61], v[98:101], v[122:125], v[58:61]
	v_mfma_f32_16x16x32_bf16 v[46:49], v[82:85], v[146:149], v[46:49]
	v_mfma_f32_16x16x32_bf16 v[42:45], v[98:101], v[146:149], v[42:45]
	s_barrier
	s_setprio 1
	v_mfma_f32_16x16x32_bf16 v[30:33], v[82:85], v[162:165], v[30:33]
	v_mfma_f32_16x16x32_bf16 v[26:29], v[98:101], v[162:165], v[26:29]
	v_mfma_f32_16x16x32_bf16 v[14:17], v[82:85], v[170:173], v[14:17]
	v_mfma_f32_16x16x32_bf16 v[10:13], v[98:101], v[170:173], v[10:13]
	v_mfma_f32_16x16x32_bf16 v[62:65], v[94:97], v[130:133], v[62:65]
	v_mfma_f32_16x16x32_bf16 v[58:61], v[114:117], v[130:133], v[58:61]
	v_mfma_f32_16x16x32_bf16 v[46:49], v[94:97], v[150:153], v[46:49]
	v_mfma_f32_16x16x32_bf16 v[42:45], v[114:117], v[150:153], v[42:45]
	v_mfma_f32_16x16x32_bf16 v[30:33], v[94:97], v[166:169], v[30:33]
	v_mfma_f32_16x16x32_bf16 v[26:29], v[114:117], v[166:169], v[26:29]
	v_mfma_f32_16x16x32_bf16 v[14:17], v[94:97], v[174:177], v[14:17]
	v_mfma_f32_16x16x32_bf16 v[10:13], v[114:117], v[174:177], v[10:13]
	v_mfma_f32_16x16x32_bf16 v[54:57], v[178:181], v[122:125], v[54:57]
	v_mfma_f32_16x16x32_bf16 v[50:53], v[186:189], v[122:125], v[50:53]
	v_mfma_f32_16x16x32_bf16 v[38:41], v[178:181], v[146:149], v[38:41]
	v_mfma_f32_16x16x32_bf16 v[34:37], v[186:189], v[146:149], v[34:37]
	v_mfma_f32_16x16x32_bf16 v[22:25], v[178:181], v[162:165], v[22:25]
	v_mfma_f32_16x16x32_bf16 v[18:21], v[186:189], v[162:165], v[18:21]
	v_mfma_f32_16x16x32_bf16 v[6:9], v[178:181], v[170:173], v[6:9]
	v_mfma_f32_16x16x32_bf16 v[2:5], v[186:189], v[170:173], v[2:5]
	v_mfma_f32_16x16x32_bf16 v[54:57], v[182:185], v[130:133], v[54:57]
	v_mfma_f32_16x16x32_bf16 v[50:53], v[190:193], v[130:133], v[50:53]
	v_mfma_f32_16x16x32_bf16 v[38:41], v[182:185], v[150:153], v[38:41]
	v_mfma_f32_16x16x32_bf16 v[34:37], v[190:193], v[150:153], v[34:37]
	v_mfma_f32_16x16x32_bf16 v[22:25], v[182:185], v[166:169], v[22:25]
	v_mfma_f32_16x16x32_bf16 v[18:21], v[190:193], v[166:169], v[18:21]
	v_mfma_f32_16x16x32_bf16 v[6:9], v[182:185], v[174:177], v[6:9]
	v_mfma_f32_16x16x32_bf16 v[2:5], v[190:193], v[174:177], v[2:5]
	s_setprio 0
	s_add_u32 s4, s4, 0x100
	s_addc_u32 s5, s5, 0
	s_add_u32 s34, s34, 0x100
	s_addc_u32 s35, s35, 0
	s_cmp_ge_u32 s14, s73
	s_mov_b32 s88, s14
	s_barrier
	s_cbranch_scc0 .LBB0_461
	v_lshl_add_u32 v214, s67, 8, v210
	v_lshl_or_b32 v206, s55, 8, v212
	v_ashrrev_i32_e32 v207, 31, v206
	v_ashrrev_i32_e32 v82, 31, v214
	v_mul_lo_u32 v215, s12, v82
	v_mul_lo_u32 v238, s13, v214
	v_mad_u64_u32 v[82:83], s[4:5], s12, v214, v[206:207]
	v_add3_u32 v83, v238, v83, v215
	v_lshl_add_u64 v[84:85], v[82:83], 1, s[6:7]
	global_load_dwordx4 v[190:193], v[84:85], off
	v_cndmask_b32_e64 v94, 0, 1, s[76:77]
	v_cmp_ne_u32_e64 s[4:5], 1, v94
	v_readfirstlane_b32 s98, v219
	s_nop 1
	s_bitcmp1_b32 s98, 8
	s_cbranch_scc1 .Lresync_x_461_p
	s_barrier
	s_branch .Lresync_x_461

; #define PG8_STAGE(bufoff, gbase, voff) do { _Pragma("unroll") for (int _i = 0; _i < 2; ++_i) \
;         __builtin_amdgcn_global_load_lds((const unsigned*)((const char*)(gbase) + (voff)[_i]), (LAS unsigned*)(lds + (bufoff) + ldsw + _i * 8192), 16, 0, 0); } while (0)
; #define PG8_LDA(dst, b, h) do { _Pragma("unroll") for (int m = 0; m < 4; ++m) _Pragma("unroll") for (int k = 0; k < 2; ++k) dst[m][k] = *(const LAS bf16x8*)(lds + PG8_SA(b, h) + aoff + m * 2048 + k * 1024); } while (0)
; #define PG8_LDB(dst, b, h) do { _Pragma("unroll") for (int n = 0; n < 2; ++n) _Pragma("unroll") for (int k = 0; k < 2; ++k) dst[n][k] = *(const LAS bf16x8*)(lds + PG8_SB(b, h) + boff + n * 2048 + k * 1024); } while (0)
; #define PG8_MMA(ai, bj, At, Bt) do { __builtin_amdgcn_s_setprio(1); _Pragma("unroll") for (int m = 0; m < 4; ++m) _Pragma("unroll") for (int n = 0; n < 2; ++n) _Pragma("unroll") for (int k = 0; k < 2; ++k) \
;         acc[ai][bj][m][n] = __builtin_amdgcn_mfma_f32_16x16x32_bf16(Bt[n][k], At[m][k], acc[ai][bj][m][n], 0, 0, 0); __builtin_amdgcn_s_setprio(0); } while (0)
; #define PG8_WAIT_V(n) asm volatile("s_waitcnt vmcnt(" #n ")" ::: "memory")
; #define PG8_WAIT_L(n) asm volatile("s_waitcnt lgkmcnt(" #n ")" ::: "memory")
; template <class Epi>
; __device__ __forceinline__ void gemm_phase(LAS unsigned char* lds, const Gemm g, const Sched& S, const Epi& E) {
;     ...
;         for (int t = 0; t < nt; t += 2) {
;             const bool last = (t == nt - 2);
;             const char* a1 = cA + (size_t)(t + 1) * kstep;
;             const char* a2 = last ? nA : cA + (size_t)(t + 2) * kstep; const char* b2 = last ? nB : cB + (size_t)(t + 2) * kstep;
;             const char* a3 = a2 + kstep; const char* b3 = b2 + kstep;
;             PG8_LDB(B0, 0, 0); PG8_SCHED; PG8_LDA(At, 0, 0); PG8_STAGE(PG8_SA(1, 1), a1 + hstepA, voffA);
;             PG8_WAIT_L(8); PG8_BAR; PG8_WAIT_L(0); PG8_MMA(0, 0, At, B0); PG8_BAR; PG8_SCHED;
;             PG8_LDB(B1, 0, 1); PG8_STAGE(PG8_SB(0, 0), b2, voffB);
;             PG8_BAR; PG8_WAIT_L(0); PG8_MMA(0, 1, At, B1); PG8_BAR;
;             PG8_LDA(At, 0, 1); PG8_STAGE(PG8_SA(0, 0), a2, voffA);
;             PG8_BAR; PG8_WAIT_L(0); PG8_MMA(1, 0, At, B0); PG8_BAR; PG8_SCHED;
;             PG8_STAGE(PG8_SB(0, 1), b2 + hstepB, voffB);
;             PG8_WAIT_V(6); PG8_BAR; PG8_MMA(1, 1, At, B1); PG8_BAR;
.Lresync_y_555:
.LBB0_555:
	s_add_i32 s14, s6, 2
	s_add_u32 s8, s4, 0x80
	s_addc_u32 s7, s5, 0
	s_add_i32 s9, 0, 0x10000
	v_add_u32_e32 v160, s9, v156
	ds_read_b128 v[142:145], v160
	ds_read_b128 v[146:149], v160 offset:1024
	ds_read_b128 v[150:153], v160 offset:2048
	ds_read_b128 v[160:163], v160 offset:3072
	s_cmp_eq_u32 s43, s6
	s_cselect_b32 s6, s57, s8
	s_cselect_b32 s7, s55, s7
	s_cselect_b32 s91, s59, s35
	s_cselect_b32 s90, s95, s34
	v_lshl_add_u64 v[192:193], s[4:5], 0, v[136:137]
	s_add_i32 m0, s33, 0xc000
	ds_read_b128 v[164:167], v159
	ds_read_b128 v[168:171], v159 offset:1024
	ds_read_b128 v[172:175], v159 offset:2048
	ds_read_b128 v[176:179], v159 offset:3072
	ds_read_b128 v[180:183], v159 offset:4096
	ds_read_b128 v[184:187], v159 offset:5120
	ds_read_b128 v[188:191], v159 offset:6144
	ds_read_b128 v[196:199], v159 offset:7168
	global_load_lds_dwordx4 v[192:193], off
	v_lshl_add_u64 v[192:193], s[4:5], 0, v[138:139]
	s_add_i32 m0, s33, 0xe000
	s_nop 0
	global_load_lds_dwordx4 v[192:193], off
	s_add_i32 s8, 0, 0x14000
	v_add_u32_e32 v192, s8, v156
	ds_read_b128 v[200:203], v192
	ds_read_b128 v[204:207], v192 offset:1024
	ds_read_b128 v[208:211], v192 offset:2048
	ds_read_b128 v[212:215], v192 offset:3072
	s_waitcnt vmcnt(8)
	s_waitcnt lgkmcnt(0)
	v_mfma_f32_16x16x32_bf16 v[126:129], v[142:145], v[164:167], v[126:129]
	v_mfma_f32_16x16x32_bf16 v[122:125], v[150:153], v[164:167], v[122:125]
	v_mfma_f32_16x16x32_bf16 v[110:113], v[142:145], v[172:175], v[110:113]
	v_mfma_f32_16x16x32_bf16 v[106:109], v[150:153], v[172:175], v[106:109]
	s_barrier
	s_setprio 1
	v_mfma_f32_16x16x32_bf16 v[94:97], v[142:145], v[180:183], v[94:97]
	v_mfma_f32_16x16x32_bf16 v[90:93], v[150:153], v[180:183], v[90:93]
	v_mfma_f32_16x16x32_bf16 v[78:81], v[142:145], v[188:191], v[78:81]
	v_mfma_f32_16x16x32_bf16 v[74:77], v[150:153], v[188:191], v[74:77]
	v_mfma_f32_16x16x32_bf16 v[126:129], v[146:149], v[168:171], v[126:129]
	v_mfma_f32_16x16x32_bf16 v[122:125], v[160:163], v[168:171], v[122:125]
	v_mfma_f32_16x16x32_bf16 v[110:113], v[146:149], v[176:179], v[110:113]
	v_mfma_f32_16x16x32_bf16 v[106:109], v[160:163], v[176:179], v[106:109]
	v_mfma_f32_16x16x32_bf16 v[94:97], v[146:149], v[184:187], v[94:97]
	v_mfma_f32_16x16x32_bf16 v[90:93], v[160:163], v[184:187], v[90:93]
	v_mfma_f32_16x16x32_bf16 v[78:81], v[146:149], v[196:199], v[78:81]
	v_mfma_f32_16x16x32_bf16 v[74:77], v[160:163], v[196:199], v[74:77]
	v_mfma_f32_16x16x32_bf16 v[118:121], v[200:203], v[164:167], v[118:121]
	v_mfma_f32_16x16x32_bf16 v[114:117], v[208:211], v[164:167], v[114:117]
	v_mfma_f32_16x16x32_bf16 v[102:105], v[200:203], v[172:175], v[102:105]
	v_mfma_f32_16x16x32_bf16 v[98:101], v[208:211], v[172:175], v[98:101]
	v_mfma_f32_16x16x32_bf16 v[86:89], v[200:203], v[180:183], v[86:89]
	v_mfma_f32_16x16x32_bf16 v[82:85], v[208:211], v[180:183], v[82:85]
	v_mfma_f32_16x16x32_bf16 v[70:73], v[200:203], v[188:191], v[70:73]
	v_mfma_f32_16x16x32_bf16 v[66:69], v[208:211], v[188:191], v[66:69]
	v_mfma_f32_16x16x32_bf16 v[118:121], v[204:207], v[168:171], v[118:121]
	v_mfma_f32_16x16x32_bf16 v[114:117], v[212:215], v[168:171], v[114:117]
	v_mfma_f32_16x16x32_bf16 v[102:105], v[204:207], v[176:179], v[102:105]
	v_mfma_f32_16x16x32_bf16 v[98:101], v[212:215], v[176:179], v[98:101]
	v_mfma_f32_16x16x32_bf16 v[86:89], v[204:207], v[184:187], v[86:89]
	v_mfma_f32_16x16x32_bf16 v[82:85], v[212:215], v[184:187], v[82:85]
	v_mfma_f32_16x16x32_bf16 v[70:73], v[204:207], v[196:199], v[70:73]
	v_mfma_f32_16x16x32_bf16 v[66:69], v[212:215], v[196:199], v[66:69]
	s_setprio 0
	s_barrier
	s_add_i32 s9, s9, s3
	v_lshl_add_u64 v[192:193], s[90:91], 0, v[0:1]
	s_mov_b32 m0, s9
	v_lshl_add_u64 v[194:195], s[90:91], 0, v[134:135]
	global_load_lds_dwordx4 v[192:193], off
	s_add_i32 m0, s9, 0x2000
	s_nop 0
	global_load_lds_dwordx4 v[194:195], off
	s_mov_b32 m0, s33
	v_lshl_add_u64 v[216:217], s[6:7], 0, v[130:131]
	ds_read_b128 v[164:167], v159 offset:16384
	ds_read_b128 v[168:171], v159 offset:17408
	ds_read_b128 v[172:175], v159 offset:18432
	ds_read_b128 v[176:179], v159 offset:19456
	ds_read_b128 v[180:183], v159 offset:20480
	ds_read_b128 v[184:187], v159 offset:21504
	ds_read_b128 v[188:191], v159 offset:22528
	ds_read_b128 v[196:199], v159 offset:23552
	global_load_lds_dwordx4 v[216:217], off
	v_lshl_add_u64 v[222:223], s[6:7], 0, v[132:133]
	s_mov_b32 m0, s38
	s_nop 0
	global_load_lds_dwordx4 v[222:223], off
	s_add_u32 s90, s90, s76
	s_addc_u32 s91, s91, s77
	s_add_i32 s8, s8, s3
	v_lshl_add_u64 v[224:225], s[90:91], 0, v[0:1]
	s_mov_b32 m0, s8
	v_lshl_add_u64 v[226:227], s[90:91], 0, v[134:135]
	global_load_lds_dwordx4 v[224:225], off
	s_add_i32 m0, s8, 0x2000
	s_nop 0
	global_load_lds_dwordx4 v[226:227], off
	s_waitcnt vmcnt(8)
	s_waitcnt lgkmcnt(0)
	v_mfma_f32_16x16x32_bf16 v[62:65], v[142:145], v[164:167], v[62:65]
	v_mfma_f32_16x16x32_bf16 v[58:61], v[150:153], v[164:167], v[58:61]
	v_mfma_f32_16x16x32_bf16 v[46:49], v[142:145], v[172:175], v[46:49]
	v_mfma_f32_16x16x32_bf16 v[42:45], v[150:153], v[172:175], v[42:45]
	s_barrier
; #define PG8_STAGE(bufoff, gbase, voff) do { _Pragma("unroll") for (int _i = 0; _i < 2; ++_i) \
;         __builtin_amdgcn_global_load_lds((const unsigned*)((const char*)(gbase) + (voff)[_i]), (LAS unsigned*)(lds + (bufoff) + ldsw + _i * 8192), 16, 0, 0); } while (0)
; #define PG8_LDA(dst, b, h) do { _Pragma("unroll") for (int m = 0; m < 4; ++m) _Pragma("unroll") for (int k = 0; k < 2; ++k) dst[m][k] = *(const LAS bf16x8*)(lds + PG8_SA(b, h) + aoff + m * 2048 + k * 1024); } while (0)
; #define PG8_LDB(dst, b, h) do { _Pragma("unroll") for (int n = 0; n < 2; ++n) _Pragma("unroll") for (int k = 0; k < 2; ++k) dst[n][k] = *(const LAS bf16x8*)(lds + PG8_SB(b, h) + boff + n * 2048 + k * 1024); } while (0)
; #define PG8_MMA(ai, bj, At, Bt) do { __builtin_amdgcn_s_setprio(1); _Pragma("unroll") for (int m = 0; m < 4; ++m) _Pragma("unroll") for (int n = 0; n < 2; ++n) _Pragma("unroll") for (int k = 0; k < 2; ++k) \
;         acc[ai][bj][m][n] = __builtin_amdgcn_mfma_f32_16x16x32_bf16(Bt[n][k], At[m][k], acc[ai][bj][m][n], 0, 0, 0); __builtin_amdgcn_s_setprio(0); } while (0)
; #define PG8_WAIT_V(n) asm volatile("s_waitcnt vmcnt(" #n ")" ::: "memory")
; #define PG8_WAIT_L(n) asm volatile("s_waitcnt lgkmcnt(" #n ")" ::: "memory")
; #define PG8_BAR __builtin_amdgcn_s_barrier()
; #define PG8_SCHED __builtin_amdgcn_sched_barrier(0)
; template <class Epi>
; __device__ __forceinline__ void gemm_phase(LAS unsigned char* lds, const Gemm g, const Sched& S, const Epi& E) {
;     ...
;             PG8_WAIT_V(6); PG8_BAR; PG8_MMA(1, 1, At, B1); PG8_BAR;
;             PG8_LDB(B0, 1, 0); PG8_SCHED; PG8_LDA(At, 1, 0); PG8_STAGE(PG8_SA(0, 1), a2 + hstepA, voffA);
;             PG8_WAIT_L(8); PG8_BAR; PG8_WAIT_L(0); PG8_MMA(0, 0, At, B0); PG8_BAR; PG8_SCHED;
;             PG8_LDB(B1, 1, 1); PG8_STAGE(PG8_SB(1, 0), b3, voffB);
;             PG8_BAR; PG8_WAIT_L(0); PG8_MMA(0, 1, At, B1); PG8_BAR;
	s_setprio 1
	v_mfma_f32_16x16x32_bf16 v[30:33], v[142:145], v[180:183], v[30:33]
	v_mfma_f32_16x16x32_bf16 v[26:29], v[150:153], v[180:183], v[26:29]
	v_mfma_f32_16x16x32_bf16 v[14:17], v[142:145], v[188:191], v[14:17]
	v_mfma_f32_16x16x32_bf16 v[10:13], v[150:153], v[188:191], v[10:13]
	v_mfma_f32_16x16x32_bf16 v[62:65], v[146:149], v[168:171], v[62:65]
	v_mfma_f32_16x16x32_bf16 v[58:61], v[160:163], v[168:171], v[58:61]
	v_mfma_f32_16x16x32_bf16 v[46:49], v[146:149], v[176:179], v[46:49]
	v_mfma_f32_16x16x32_bf16 v[42:45], v[160:163], v[176:179], v[42:45]
	v_mfma_f32_16x16x32_bf16 v[30:33], v[146:149], v[184:187], v[30:33]
	v_mfma_f32_16x16x32_bf16 v[26:29], v[160:163], v[184:187], v[26:29]
	v_mfma_f32_16x16x32_bf16 v[14:17], v[146:149], v[196:199], v[14:17]
	v_mfma_f32_16x16x32_bf16 v[10:13], v[160:163], v[196:199], v[10:13]
	v_mfma_f32_16x16x32_bf16 v[54:57], v[200:203], v[164:167], v[54:57]
	v_mfma_f32_16x16x32_bf16 v[50:53], v[208:211], v[164:167], v[50:53]
	v_mfma_f32_16x16x32_bf16 v[38:41], v[200:203], v[172:175], v[38:41]
	v_mfma_f32_16x16x32_bf16 v[34:37], v[208:211], v[172:175], v[34:37]
	v_mfma_f32_16x16x32_bf16 v[22:25], v[200:203], v[180:183], v[22:25]
	v_mfma_f32_16x16x32_bf16 v[18:21], v[208:211], v[180:183], v[18:21]
	v_mfma_f32_16x16x32_bf16 v[6:9], v[200:203], v[188:191], v[6:9]
	v_mfma_f32_16x16x32_bf16 v[2:5], v[208:211], v[188:191], v[2:5]
	v_mfma_f32_16x16x32_bf16 v[54:57], v[204:207], v[168:171], v[54:57]
	v_mfma_f32_16x16x32_bf16 v[50:53], v[212:215], v[168:171], v[50:53]
	v_mfma_f32_16x16x32_bf16 v[38:41], v[204:207], v[176:179], v[38:41]
	v_mfma_f32_16x16x32_bf16 v[34:37], v[212:215], v[176:179], v[34:37]
	v_mfma_f32_16x16x32_bf16 v[22:25], v[204:207], v[184:187], v[22:25]
	v_mfma_f32_16x16x32_bf16 v[18:21], v[212:215], v[184:187], v[18:21]
	v_mfma_f32_16x16x32_bf16 v[6:9], v[204:207], v[196:199], v[6:9]
	v_mfma_f32_16x16x32_bf16 v[2:5], v[212:215], v[196:199], v[2:5]
	s_setprio 0
	s_barrier
	s_add_i32 s8, 0, 0x18000
	v_add_u32_e32 v160, s8, v156
	ds_read_b128 v[142:145], v160
	ds_read_b128 v[146:149], v160 offset:1024
	ds_read_b128 v[150:153], v160 offset:2048
	ds_read_b128 v[160:163], v160 offset:3072
	s_add_u32 s6, s6, s36
	s_addc_u32 s7, s7, s37
	s_mov_b32 m0, s39
	v_lshl_add_u64 v[200:201], s[6:7], 0, v[130:131]
	ds_read_b128 v[164:167], v159 offset:32768
	ds_read_b128 v[168:171], v159 offset:33792
	ds_read_b128 v[172:175], v159 offset:34816
	ds_read_b128 v[176:179], v159 offset:35840
	ds_read_b128 v[180:183], v159 offset:36864
	ds_read_b128 v[184:187], v159 offset:37888
	ds_read_b128 v[188:191], v159 offset:38912
	ds_read_b128 v[196:199], v159 offset:39936
	global_load_lds_dwordx4 v[200:201], off
	v_lshl_add_u64 v[200:201], s[6:7], 0, v[132:133]
	s_mov_b32 m0, s40
	s_nop 0
	global_load_lds_dwordx4 v[200:201], off
	s_add_i32 s6, 0, 0x1c000
	v_add_u32_e32 v212, s6, v156
	ds_read_b128 v[200:203], v212
	ds_read_b128 v[204:207], v212 offset:1024
	ds_read_b128 v[208:211], v212 offset:2048
	ds_read_b128 v[212:215], v212 offset:3072
	s_waitcnt vmcnt(8)
	s_waitcnt lgkmcnt(0)
	v_mfma_f32_16x16x32_bf16 v[126:129], v[142:145], v[164:167], v[126:129]
	v_mfma_f32_16x16x32_bf16 v[122:125], v[150:153], v[164:167], v[122:125]
	v_mfma_f32_16x16x32_bf16 v[110:113], v[142:145], v[172:175], v[110:113]
	v_mfma_f32_16x16x32_bf16 v[106:109], v[150:153], v[172:175], v[106:109]
	s_barrier
	s_setprio 1
	v_mfma_f32_16x16x32_bf16 v[94:97], v[142:145], v[180:183], v[94:97]
	v_mfma_f32_16x16x32_bf16 v[90:93], v[150:153], v[180:183], v[90:93]
	v_mfma_f32_16x16x32_bf16 v[78:81], v[142:145], v[188:191], v[78:81]
	v_mfma_f32_16x16x32_bf16 v[74:77], v[150:153], v[188:191], v[74:77]
	v_mfma_f32_16x16x32_bf16 v[126:129], v[146:149], v[168:171], v[126:129]
	v_mfma_f32_16x16x32_bf16 v[122:125], v[160:163], v[168:171], v[122:125]
	v_mfma_f32_16x16x32_bf16 v[110:113], v[146:149], v[176:179], v[110:113]
	v_mfma_f32_16x16x32_bf16 v[106:109], v[160:163], v[176:179], v[106:109]
	v_mfma_f32_16x16x32_bf16 v[94:97], v[146:149], v[184:187], v[94:97]
	v_mfma_f32_16x16x32_bf16 v[90:93], v[160:163], v[184:187], v[90:93]
	v_mfma_f32_16x16x32_bf16 v[78:81], v[146:149], v[196:199], v[78:81]
	v_mfma_f32_16x16x32_bf16 v[74:77], v[160:163], v[196:199], v[74:77]
	v_mfma_f32_16x16x32_bf16 v[118:121], v[200:203], v[164:167], v[118:121]
	v_mfma_f32_16x16x32_bf16 v[114:117], v[208:211], v[164:167], v[114:117]
	v_mfma_f32_16x16x32_bf16 v[102:105], v[200:203], v[172:175], v[102:105]
	v_mfma_f32_16x16x32_bf16 v[98:101], v[208:211], v[172:175], v[98:101]
	v_mfma_f32_16x16x32_bf16 v[86:89], v[200:203], v[180:183], v[86:89]
	v_mfma_f32_16x16x32_bf16 v[82:85], v[208:211], v[180:183], v[82:85]
	v_mfma_f32_16x16x32_bf16 v[70:73], v[200:203], v[188:191], v[70:73]
	v_mfma_f32_16x16x32_bf16 v[66:69], v[208:211], v[188:191], v[66:69]
	v_mfma_f32_16x16x32_bf16 v[118:121], v[204:207], v[168:171], v[118:121]
	v_mfma_f32_16x16x32_bf16 v[114:117], v[212:215], v[168:171], v[114:117]
	v_mfma_f32_16x16x32_bf16 v[102:105], v[204:207], v[176:179], v[102:105]
	v_mfma_f32_16x16x32_bf16 v[98:101], v[212:215], v[176:179], v[98:101]
	v_mfma_f32_16x16x32_bf16 v[86:89], v[204:207], v[184:187], v[86:89]
	v_mfma_f32_16x16x32_bf16 v[82:85], v[212:215], v[184:187], v[82:85]
	v_mfma_f32_16x16x32_bf16 v[70:73], v[204:207], v[196:199], v[70:73]
	v_mfma_f32_16x16x32_bf16 v[66:69], v[212:215], v[196:199], v[66:69]
	s_setprio 0
	s_barrier
; __device__ __forceinline__ float pre_get(const Pre& p, int ai, int m, int fr) { return __shfl(p.v[ai], m * 16 + fr); }
; __device__ __forceinline__ float rstd_pre(const float* ss, float v) { return ss ? rsqrtf(v * (1.0f / 2048.0f) + 1e-6f) : 1.0f; }
; #define PG8_STAGE(bufoff, gbase, voff) do { _Pragma("unroll") for (int _i = 0; _i < 2; ++_i) \
;         __builtin_amdgcn_global_load_lds((const unsigned*)((const char*)(gbase) + (voff)[_i]), (LAS unsigned*)(lds + (bufoff) + ldsw + _i * 8192), 16, 0, 0); } while (0)
; #define PG8_LDA(dst, b, h) do { _Pragma("unroll") for (int m = 0; m < 4; ++m) _Pragma("unroll") for (int k = 0; k < 2; ++k) dst[m][k] = *(const LAS bf16x8*)(lds + PG8_SA(b, h) + aoff + m * 2048 + k * 1024); } while (0)
; #define PG8_WAIT_V(n) asm volatile("s_waitcnt vmcnt(" #n ")" ::: "memory")
; #define PG8_WAIT_L(n) asm volatile("s_waitcnt lgkmcnt(" #n ")" ::: "memory")
; #define PG8_BAR __builtin_amdgcn_s_barrier()
; #define PG8_SCHED __builtin_amdgcn_sched_barrier(0)
; template <class Epi>
; __device__ __forceinline__ void gemm_phase(LAS unsigned char* lds, const Gemm g, const Sched& S, const Epi& E) {
;     ...
;             PG8_LDA(At, 1, 1); PG8_STAGE(PG8_SA(1, 0), a3, voffA);
;             PG8_BAR; PG8_WAIT_L(0); PG8_MMA(1, 0, At, B0); PG8_BAR; PG8_SCHED;
;             PG8_STAGE(PG8_SB(1, 1), b3 + hstepB, voffB);
;             PG8_WAIT_V(6); PG8_BAR; PG8_MMA(1, 1, At, B1); PG8_BAR;
;         }
;     __device__ __forceinline__ void operator()(const Acc& acc, const Unit& u, int wr, int wc, int fr, int fq, const Pre& pre) const {
;         const int colt = (u.pn < split) ? base0 + u.pn * 256 : base1 + (u.pn - split) * 256;
;         const int row0 = u.pm * 256 + wr * 64 + fr, col0 = colt + wc * 32 + 8 * fq;
;         bf16_t* Oz = O + (size_t)(u.zb * sOb + u.zh * sOh);
;         float rsq[2][4];
; #pragma unroll
;         for (int ai = 0; ai < 2; ++ai)
; #pragma unroll
;             for (int m = 0; m < 4; ++m) rsq[ai][m] = rstd_pre(ss, pre_get(pre, ai, m, fr));
; #pragma unroll
;         for (int ai = 0; ai < 2; ++ai)
; #pragma unroll
;             for (int m = 0; m < 4; ++m) { const float rs = scale * rsq[ai][m];
; #pragma unroll
;                 for (int bj = 0; bj < 2; ++bj) { f32x4 v0 = acc[ai][bj][m][0] * rs, v1 = acc[ai][bj][m][1] * rs;
	s_add_i32 s7, s8, s3
	v_lshl_add_u64 v[192:193], v[192:193], 0, s[60:61]
	s_mov_b32 m0, s7
	s_nop 0
	global_load_lds_dwordx4 v[192:193], off
	v_lshl_add_u64 v[192:193], v[194:195], 0, s[60:61]
	s_add_i32 m0, s7, 0x2000
	s_nop 0
	global_load_lds_dwordx4 v[192:193], off
	s_mov_b32 m0, s41
	v_lshl_add_u64 v[192:193], v[216:217], 0, s[60:61]
	ds_read_b128 v[164:167], v159 offset:49152
	ds_read_b128 v[168:171], v159 offset:50176
	ds_read_b128 v[172:175], v159 offset:51200
	ds_read_b128 v[176:179], v159 offset:52224
	ds_read_b128 v[180:183], v159 offset:53248
	ds_read_b128 v[184:187], v159 offset:54272
	ds_read_b128 v[188:191], v159 offset:55296
	ds_read_b128 v[196:199], v159 offset:56320
	global_load_lds_dwordx4 v[192:193], off
	v_lshl_add_u64 v[192:193], v[222:223], 0, s[60:61]
	s_mov_b32 m0, s42
	s_nop 0
	global_load_lds_dwordx4 v[192:193], off
	s_add_i32 s6, s6, s3
	v_lshl_add_u64 v[192:193], v[224:225], 0, s[60:61]
	s_mov_b32 m0, s6
	s_nop 0
	global_load_lds_dwordx4 v[192:193], off
	v_lshl_add_u64 v[192:193], v[226:227], 0, s[60:61]
	s_add_i32 m0, s6, 0x2000
	s_nop 0
	global_load_lds_dwordx4 v[192:193], off
	s_waitcnt vmcnt(8)
	s_waitcnt lgkmcnt(0)
	v_mfma_f32_16x16x32_bf16 v[62:65], v[142:145], v[164:167], v[62:65]
	v_mfma_f32_16x16x32_bf16 v[58:61], v[150:153], v[164:167], v[58:61]
	v_mfma_f32_16x16x32_bf16 v[46:49], v[142:145], v[172:175], v[46:49]
	v_mfma_f32_16x16x32_bf16 v[42:45], v[150:153], v[172:175], v[42:45]
	s_barrier
	s_setprio 1
	v_mfma_f32_16x16x32_bf16 v[30:33], v[142:145], v[180:183], v[30:33]
	v_mfma_f32_16x16x32_bf16 v[26:29], v[150:153], v[180:183], v[26:29]
	v_mfma_f32_16x16x32_bf16 v[14:17], v[142:145], v[188:191], v[14:17]
	v_mfma_f32_16x16x32_bf16 v[10:13], v[150:153], v[188:191], v[10:13]
	v_mfma_f32_16x16x32_bf16 v[62:65], v[146:149], v[168:171], v[62:65]
	v_mfma_f32_16x16x32_bf16 v[58:61], v[160:163], v[168:171], v[58:61]
	v_mfma_f32_16x16x32_bf16 v[46:49], v[146:149], v[176:179], v[46:49]
	v_mfma_f32_16x16x32_bf16 v[42:45], v[160:163], v[176:179], v[42:45]
	v_mfma_f32_16x16x32_bf16 v[30:33], v[146:149], v[184:187], v[30:33]
	v_mfma_f32_16x16x32_bf16 v[26:29], v[160:163], v[184:187], v[26:29]
	v_mfma_f32_16x16x32_bf16 v[14:17], v[146:149], v[196:199], v[14:17]
	v_mfma_f32_16x16x32_bf16 v[10:13], v[160:163], v[196:199], v[10:13]
	v_mfma_f32_16x16x32_bf16 v[54:57], v[200:203], v[164:167], v[54:57]
	v_mfma_f32_16x16x32_bf16 v[50:53], v[208:211], v[164:167], v[50:53]
	v_mfma_f32_16x16x32_bf16 v[38:41], v[200:203], v[172:175], v[38:41]
	v_mfma_f32_16x16x32_bf16 v[34:37], v[208:211], v[172:175], v[34:37]
	v_mfma_f32_16x16x32_bf16 v[22:25], v[200:203], v[180:183], v[22:25]
	v_mfma_f32_16x16x32_bf16 v[18:21], v[208:211], v[180:183], v[18:21]
	v_mfma_f32_16x16x32_bf16 v[6:9], v[200:203], v[188:191], v[6:9]
	v_mfma_f32_16x16x32_bf16 v[2:5], v[208:211], v[188:191], v[2:5]
	v_mfma_f32_16x16x32_bf16 v[54:57], v[204:207], v[168:171], v[54:57]
	v_mfma_f32_16x16x32_bf16 v[50:53], v[212:215], v[168:171], v[50:53]
	v_mfma_f32_16x16x32_bf16 v[38:41], v[204:207], v[176:179], v[38:41]
	v_mfma_f32_16x16x32_bf16 v[34:37], v[212:215], v[176:179], v[34:37]
	v_mfma_f32_16x16x32_bf16 v[22:25], v[204:207], v[184:187], v[22:25]
	v_mfma_f32_16x16x32_bf16 v[18:21], v[212:215], v[184:187], v[18:21]
	v_mfma_f32_16x16x32_bf16 v[6:9], v[204:207], v[196:199], v[6:9]
	v_mfma_f32_16x16x32_bf16 v[2:5], v[212:215], v[196:199], v[2:5]
	s_setprio 0
	s_add_u32 s4, s4, 0x100
	s_addc_u32 s5, s5, 0
	s_add_u32 s34, s34, 0x100
	s_addc_u32 s35, s35, 0
	s_cmp_ge_u32 s14, s73
	s_mov_b32 s6, s14
	s_barrier
	s_cbranch_scc0 .LBB0_555
	v_and_or_b32 v142, v220, 64, v154
	v_lshlrev_b32_e32 v148, 2, v142
	ds_bpermute_b32 v143, v148, v141
	ds_bpermute_b32 v142, v148, v141 offset:64
	s_mov_b32 s4, 0x3a000000
	ds_bpermute_b32 v145, v148, v141 offset:128
	ds_bpermute_b32 v144, v148, v141 offset:192
	v_readlane_b32 s8, v254, 29
	s_waitcnt lgkmcnt(0)
	v_pk_fma_f32 v[146:147], v[142:143], s[4:5], v[232:233] op_sel_hi:[1,0,0]
	ds_bpermute_b32 v143, v148, v140
	v_mul_f32_e32 v141, 0x4b800000, v147
	v_cmp_gt_f32_e32 vcc, s97, v147
	ds_bpermute_b32 v142, v148, v140 offset:64
	v_readlane_b32 s9, v254, 30
	v_cndmask_b32_e32 v141, v147, v141, vcc
	v_rsq_f32_e32 v141, v141
	v_cmp_gt_f32_e64 s[4:5], s97, v146
	s_mov_b64 s[90:91], -1
	v_mul_f32_e32 v147, 0x45800000, v141
	v_cndmask_b32_e32 v141, v141, v147, vcc
	v_cndmask_b32_e64 v147, v141, 1.0, s[78:79]
	ds_bpermute_b32 v141, v148, v140 offset:128
	ds_bpermute_b32 v140, v148, v140 offset:192
	v_mul_f32_e32 v148, s70, v147
	v_pk_mul_f32 v[152:153], v[122:123], v[148:149] op_sel_hi:[1,0]
	v_cndmask_b32_e64 v122, 0, 1, s[8:9]
	v_pk_mul_f32 v[128:129], v[128:129], v[148:149] op_sel_hi:[1,0]
	v_pk_mul_f32 v[150:151], v[126:127], v[148:149] op_sel_hi:[1,0]
	v_pk_mul_f32 v[126:127], v[124:125], v[148:149] op_sel_hi:[1,0]
	v_cmp_ne_u32_e64 s[6:7], 1, v122
	v_readfirstlane_b32 s98, v219
	s_nop 1
	s_bitcmp1_b32 s98, 8
	s_cbranch_scc1 .Lresync_x_555_p
	s_barrier
	s_branch .Lresync_x_555

; #define PG8_STAGE(bufoff, gbase, voff) do { _Pragma("unroll") for (int _i = 0; _i < 2; ++_i) \
;         __builtin_amdgcn_global_load_lds((const unsigned*)((const char*)(gbase) + (voff)[_i]), (LAS unsigned*)(lds + (bufoff) + ldsw + _i * 8192), 16, 0, 0); } while (0)
; #define PG8_LDA(dst, b, h) do { _Pragma("unroll") for (int m = 0; m < 4; ++m) _Pragma("unroll") for (int k = 0; k < 2; ++k) dst[m][k] = *(const LAS bf16x8*)(lds + PG8_SA(b, h) + aoff + m * 2048 + k * 1024); } while (0)
; #define PG8_LDB(dst, b, h) do { _Pragma("unroll") for (int n = 0; n < 2; ++n) _Pragma("unroll") for (int k = 0; k < 2; ++k) dst[n][k] = *(const LAS bf16x8*)(lds + PG8_SB(b, h) + boff + n * 2048 + k * 1024); } while (0)
; #define PG8_MMA(ai, bj, At, Bt) do { __builtin_amdgcn_s_setprio(1); _Pragma("unroll") for (int m = 0; m < 4; ++m) _Pragma("unroll") for (int n = 0; n < 2; ++n) _Pragma("unroll") for (int k = 0; k < 2; ++k) \
;         acc[ai][bj][m][n] = __builtin_amdgcn_mfma_f32_16x16x32_bf16(Bt[n][k], At[m][k], acc[ai][bj][m][n], 0, 0, 0); __builtin_amdgcn_s_setprio(0); } while (0)
; #define PG8_WAIT_V(n) asm volatile("s_waitcnt vmcnt(" #n ")" ::: "memory")
; #define PG8_WAIT_L(n) asm volatile("s_waitcnt lgkmcnt(" #n ")" ::: "memory")
; template <class Epi>
; __device__ __forceinline__ void gemm_phase(LAS unsigned char* lds, const Gemm g, const Sched& S, const Epi& E) {
;     ...
;         for (int t = 0; t < nt; t += 2) {
;             const bool last = (t == nt - 2);
;             const char* a1 = cA + (size_t)(t + 1) * kstep;
;             const char* a2 = last ? nA : cA + (size_t)(t + 2) * kstep; const char* b2 = last ? nB : cB + (size_t)(t + 2) * kstep;
;             const char* a3 = a2 + kstep; const char* b3 = b2 + kstep;
;             PG8_LDB(B0, 0, 0); PG8_SCHED; PG8_LDA(At, 0, 0); PG8_STAGE(PG8_SA(1, 1), a1 + hstepA, voffA);
;             PG8_WAIT_L(8); PG8_BAR; PG8_WAIT_L(0); PG8_MMA(0, 0, At, B0); PG8_BAR; PG8_SCHED;
;             PG8_LDB(B1, 0, 1); PG8_STAGE(PG8_SB(0, 0), b2, voffB);
;             PG8_BAR; PG8_WAIT_L(0); PG8_MMA(0, 1, At, B1); PG8_BAR;
;             PG8_LDA(At, 0, 1); PG8_STAGE(PG8_SA(0, 0), a2, voffA);
;             PG8_BAR; PG8_WAIT_L(0); PG8_MMA(1, 0, At, B0); PG8_BAR; PG8_SCHED;
;             PG8_STAGE(PG8_SB(0, 1), b2 + hstepB, voffB);
;             PG8_WAIT_V(6); PG8_BAR; PG8_MMA(1, 1, At, B1); PG8_BAR;
.Lresync_y_719:
.LBB0_719:
	s_add_i32 s14, s4, 2
	s_add_u32 s15, s0, 0x80
	s_addc_u32 s5, s1, 0
	s_add_i32 s8, 0, 0x10000
	v_add_u32_e32 v118, s8, v217
	ds_read_b128 v[106:109], v118
	ds_read_b128 v[110:113], v118 offset:1024
	ds_read_b128 v[114:117], v118 offset:2048
	ds_read_b128 v[118:121], v118 offset:3072
	s_cmp_eq_u32 s48, s4
	s_cselect_b32 s4, s59, s15
	s_cselect_b32 s5, s57, s5
	s_cselect_b32 s95, vcc_lo, s35
	s_cselect_b32 s94, vcc_hi, s34
	v_lshl_add_u64 v[154:155], s[0:1], 0, v[202:203]
	s_add_i32 m0, s52, 0xc000
	ds_read_b128 v[122:125], v235
	ds_read_b128 v[126:129], v235 offset:1024
	ds_read_b128 v[130:133], v235 offset:2048
	ds_read_b128 v[134:137], v235 offset:3072
	ds_read_b128 v[138:141], v235 offset:4096
	ds_read_b128 v[142:145], v235 offset:5120
	ds_read_b128 v[146:149], v235 offset:6144
	ds_read_b128 v[150:153], v235 offset:7168
	global_load_lds_dwordx4 v[154:155], off
	v_lshl_add_u64 v[154:155], s[0:1], 0, v[204:205]
	s_add_i32 m0, s52, 0xe000
	s_nop 0
	global_load_lds_dwordx4 v[154:155], off
	s_waitcnt lgkmcnt(8)
	s_waitcnt lgkmcnt(0)
	v_mfma_f32_16x16x32_bf16 v[162:165], v[114:117], v[130:133], v[162:165]
	v_mfma_f32_16x16x32_bf16 v[94:97], v[106:109], v[138:141], v[94:97]
	v_mfma_f32_16x16x32_bf16 v[90:93], v[114:117], v[138:141], v[90:93]
	v_mfma_f32_16x16x32_bf16 v[78:81], v[106:109], v[146:149], v[78:81]
	s_barrier
	s_waitcnt lgkmcnt(0)
	s_setprio 1
	s_waitcnt lgkmcnt(0)
	v_mfma_f32_16x16x32_bf16 v[74:77], v[114:117], v[146:149], v[74:77]
	v_mfma_f32_16x16x32_bf16 v[154:157], v[106:109], v[122:125], v[190:193]
	v_mfma_f32_16x16x32_bf16 v[158:161], v[114:117], v[122:125], v[186:189]
	v_mfma_f32_16x16x32_bf16 v[166:169], v[106:109], v[130:133], v[174:177]
	v_mfma_f32_16x16x32_bf16 v[162:165], v[118:121], v[134:137], v[162:165]
	v_mfma_f32_16x16x32_bf16 v[94:97], v[110:113], v[142:145], v[94:97]
	v_mfma_f32_16x16x32_bf16 v[90:93], v[118:121], v[142:145], v[90:93]
	v_mfma_f32_16x16x32_bf16 v[78:81], v[110:113], v[150:153], v[78:81]
	v_mfma_f32_16x16x32_bf16 v[74:77], v[118:121], v[150:153], v[74:77]
	v_mfma_f32_16x16x32_bf16 v[154:157], v[110:113], v[126:129], v[154:157]
	v_mfma_f32_16x16x32_bf16 v[158:161], v[118:121], v[126:129], v[158:161]
	v_mfma_f32_16x16x32_bf16 v[166:169], v[110:113], v[134:137], v[166:169]
	s_setprio 0
	s_barrier
	s_add_i32 s9, 0, 0x14000
	s_add_i32 s8, s8, s43
	v_add_u32_e32 v190, s9, v217
	v_lshl_add_u64 v[210:211], s[94:95], 0, v[0:1]
	s_mov_b32 m0, s8
	ds_read_b128 v[170:173], v190
	ds_read_b128 v[174:177], v190 offset:1024
	ds_read_b128 v[186:189], v190 offset:2048
	ds_read_b128 v[190:193], v190 offset:3072
	global_load_lds_dwordx4 v[210:211], off
	v_lshl_add_u64 v[212:213], s[94:95], 0, v[200:201]
	s_add_i32 m0, s8, 0x2000
	s_nop 0
	global_load_lds_dwordx4 v[212:213], off
	s_waitcnt lgkmcnt(0)
	v_mfma_f32_16x16x32_bf16 v[182:185], v[170:173], v[122:125], v[182:185]
	v_mfma_f32_16x16x32_bf16 v[102:105], v[170:173], v[130:133], v[102:105]
	v_mfma_f32_16x16x32_bf16 v[98:101], v[186:189], v[130:133], v[98:101]
	v_mfma_f32_16x16x32_bf16 v[86:89], v[170:173], v[138:141], v[86:89]
	s_barrier
	s_waitcnt lgkmcnt(0)
	s_setprio 1
	s_waitcnt lgkmcnt(0)
	v_mfma_f32_16x16x32_bf16 v[82:85], v[186:189], v[138:141], v[82:85]
	v_mfma_f32_16x16x32_bf16 v[70:73], v[170:173], v[146:149], v[70:73]
	v_mfma_f32_16x16x32_bf16 v[66:69], v[186:189], v[146:149], v[66:69]
	v_mfma_f32_16x16x32_bf16 v[182:185], v[174:177], v[126:129], v[182:185]
	v_mfma_f32_16x16x32_bf16 v[122:125], v[186:189], v[122:125], v[178:181]
	v_mfma_f32_16x16x32_bf16 v[102:105], v[174:177], v[134:137], v[102:105]
	v_mfma_f32_16x16x32_bf16 v[98:101], v[190:193], v[134:137], v[98:101]
	v_mfma_f32_16x16x32_bf16 v[86:89], v[174:177], v[142:145], v[86:89]
	v_mfma_f32_16x16x32_bf16 v[82:85], v[190:193], v[142:145], v[82:85]
	v_mfma_f32_16x16x32_bf16 v[70:73], v[174:177], v[150:153], v[70:73]
	v_mfma_f32_16x16x32_bf16 v[66:69], v[190:193], v[150:153], v[66:69]
	v_mfma_f32_16x16x32_bf16 v[122:125], v[190:193], v[126:129], v[122:125]
	s_setprio 0
	s_mov_b32 m0, s52
	v_lshl_add_u64 v[214:215], s[4:5], 0, v[196:197]
	s_barrier
	ds_read_b128 v[126:129], v235 offset:16384
	ds_read_b128 v[130:133], v235 offset:17408
	ds_read_b128 v[134:137], v235 offset:18432
	ds_read_b128 v[138:141], v235 offset:19456
	ds_read_b128 v[142:145], v235 offset:20480
	ds_read_b128 v[146:149], v235 offset:21504
	ds_read_b128 v[150:153], v235 offset:22528
	ds_read_b128 v[178:181], v235 offset:23552
	global_load_lds_dwordx4 v[214:215], off
	v_lshl_add_u64 v[222:223], s[4:5], 0, v[198:199]
	s_mov_b32 m0, s53
	s_nop 0
	global_load_lds_dwordx4 v[222:223], off
	s_add_u32 s94, s94, s76
	s_addc_u32 s95, s95, s77
	s_add_i32 s8, s9, s43
	v_lshl_add_u64 v[224:225], s[94:95], 0, v[0:1]
	s_mov_b32 m0, s8
	v_lshl_add_u64 v[226:227], s[94:95], 0, v[200:201]
	global_load_lds_dwordx4 v[224:225], off
	s_add_i32 m0, s8, 0x2000
	s_nop 0
	global_load_lds_dwordx4 v[226:227], off
	s_waitcnt vmcnt(6)
	s_waitcnt lgkmcnt(0)
	v_mfma_f32_16x16x32_bf16 v[62:65], v[106:109], v[126:129], v[62:65]
	v_mfma_f32_16x16x32_bf16 v[58:61], v[114:117], v[126:129], v[58:61]
	v_mfma_f32_16x16x32_bf16 v[46:49], v[106:109], v[134:137], v[46:49]
	v_mfma_f32_16x16x32_bf16 v[42:45], v[114:117], v[134:137], v[42:45]
	s_barrier
; #define PG8_STAGE(bufoff, gbase, voff) do { _Pragma("unroll") for (int _i = 0; _i < 2; ++_i) \
;         __builtin_amdgcn_global_load_lds((const unsigned*)((const char*)(gbase) + (voff)[_i]), (LAS unsigned*)(lds + (bufoff) + ldsw + _i * 8192), 16, 0, 0); } while (0)
; #define PG8_LDA(dst, b, h) do { _Pragma("unroll") for (int m = 0; m < 4; ++m) _Pragma("unroll") for (int k = 0; k < 2; ++k) dst[m][k] = *(const LAS bf16x8*)(lds + PG8_SA(b, h) + aoff + m * 2048 + k * 1024); } while (0)
; #define PG8_LDB(dst, b, h) do { _Pragma("unroll") for (int n = 0; n < 2; ++n) _Pragma("unroll") for (int k = 0; k < 2; ++k) dst[n][k] = *(const LAS bf16x8*)(lds + PG8_SB(b, h) + boff + n * 2048 + k * 1024); } while (0)
; #define PG8_MMA(ai, bj, At, Bt) do { __builtin_amdgcn_s_setprio(1); _Pragma("unroll") for (int m = 0; m < 4; ++m) _Pragma("unroll") for (int n = 0; n < 2; ++n) _Pragma("unroll") for (int k = 0; k < 2; ++k) \
;         acc[ai][bj][m][n] = __builtin_amdgcn_mfma_f32_16x16x32_bf16(Bt[n][k], At[m][k], acc[ai][bj][m][n], 0, 0, 0); __builtin_amdgcn_s_setprio(0); } while (0)
; #define PG8_WAIT_V(n) asm volatile("s_waitcnt vmcnt(" #n ")" ::: "memory")
; #define PG8_WAIT_L(n) asm volatile("s_waitcnt lgkmcnt(" #n ")" ::: "memory")
; #define PG8_BAR __builtin_amdgcn_s_barrier()
; #define PG8_SCHED __builtin_amdgcn_sched_barrier(0)
; template <class Epi>
; __device__ __forceinline__ void gemm_phase(LAS unsigned char* lds, const Gemm g, const Sched& S, const Epi& E) {
;     ...
;             PG8_WAIT_V(6); PG8_BAR; PG8_MMA(1, 1, At, B1); PG8_BAR;
;             PG8_LDB(B0, 1, 0); PG8_SCHED; PG8_LDA(At, 1, 0); PG8_STAGE(PG8_SA(0, 1), a2 + hstepA, voffA);
;             PG8_WAIT_L(8); PG8_BAR; PG8_WAIT_L(0); PG8_MMA(0, 0, At, B0); PG8_BAR; PG8_SCHED;
;             PG8_LDB(B1, 1, 1); PG8_STAGE(PG8_SB(1, 0), b3, voffB);
;             PG8_BAR; PG8_WAIT_L(0); PG8_MMA(0, 1, At, B1); PG8_BAR;
	s_setprio 1
	v_mfma_f32_16x16x32_bf16 v[30:33], v[106:109], v[142:145], v[30:33]
	v_mfma_f32_16x16x32_bf16 v[26:29], v[114:117], v[142:145], v[26:29]
	v_mfma_f32_16x16x32_bf16 v[14:17], v[106:109], v[150:153], v[14:17]
	v_mfma_f32_16x16x32_bf16 v[10:13], v[114:117], v[150:153], v[10:13]
	v_mfma_f32_16x16x32_bf16 v[62:65], v[110:113], v[130:133], v[62:65]
	v_mfma_f32_16x16x32_bf16 v[58:61], v[118:121], v[130:133], v[58:61]
	v_mfma_f32_16x16x32_bf16 v[46:49], v[110:113], v[138:141], v[46:49]
	v_mfma_f32_16x16x32_bf16 v[42:45], v[118:121], v[138:141], v[42:45]
	v_mfma_f32_16x16x32_bf16 v[30:33], v[110:113], v[146:149], v[30:33]
	v_mfma_f32_16x16x32_bf16 v[26:29], v[118:121], v[146:149], v[26:29]
	v_mfma_f32_16x16x32_bf16 v[14:17], v[110:113], v[178:181], v[14:17]
	v_mfma_f32_16x16x32_bf16 v[10:13], v[118:121], v[178:181], v[10:13]
	v_mfma_f32_16x16x32_bf16 v[54:57], v[170:173], v[126:129], v[54:57]
	v_mfma_f32_16x16x32_bf16 v[50:53], v[186:189], v[126:129], v[50:53]
	v_mfma_f32_16x16x32_bf16 v[38:41], v[170:173], v[134:137], v[38:41]
	v_mfma_f32_16x16x32_bf16 v[34:37], v[186:189], v[134:137], v[34:37]
	v_mfma_f32_16x16x32_bf16 v[22:25], v[170:173], v[142:145], v[22:25]
	v_mfma_f32_16x16x32_bf16 v[18:21], v[186:189], v[142:145], v[18:21]
	v_mfma_f32_16x16x32_bf16 v[6:9], v[170:173], v[150:153], v[6:9]
	v_mfma_f32_16x16x32_bf16 v[2:5], v[186:189], v[150:153], v[2:5]
	v_mfma_f32_16x16x32_bf16 v[54:57], v[174:177], v[130:133], v[54:57]
	v_mfma_f32_16x16x32_bf16 v[50:53], v[190:193], v[130:133], v[50:53]
	v_mfma_f32_16x16x32_bf16 v[38:41], v[174:177], v[138:141], v[38:41]
	v_mfma_f32_16x16x32_bf16 v[34:37], v[190:193], v[138:141], v[34:37]
	v_mfma_f32_16x16x32_bf16 v[22:25], v[174:177], v[146:149], v[22:25]
	v_mfma_f32_16x16x32_bf16 v[18:21], v[190:193], v[146:149], v[18:21]
	v_mfma_f32_16x16x32_bf16 v[6:9], v[174:177], v[178:181], v[6:9]
	v_mfma_f32_16x16x32_bf16 v[2:5], v[190:193], v[178:181], v[2:5]
	s_setprio 0
	s_add_i32 s8, 0, 0x18000
	v_add_u32_e32 v118, s8, v217
	s_barrier
	ds_read_b128 v[106:109], v118
	ds_read_b128 v[110:113], v118 offset:1024
	ds_read_b128 v[114:117], v118 offset:2048
	ds_read_b128 v[118:121], v118 offset:3072
	s_add_u32 s4, s4, s40
	s_addc_u32 s5, s5, s41
	s_mov_b32 m0, s56
	v_lshl_add_u64 v[174:175], s[4:5], 0, v[196:197]
	ds_read_b128 v[126:129], v235 offset:32768
	ds_read_b128 v[130:133], v235 offset:33792
	ds_read_b128 v[134:137], v235 offset:34816
	ds_read_b128 v[138:141], v235 offset:35840
	ds_read_b128 v[142:145], v235 offset:36864
	ds_read_b128 v[146:149], v235 offset:37888
	ds_read_b128 v[150:153], v235 offset:38912
	ds_read_b128 v[170:173], v235 offset:39936
	global_load_lds_dwordx4 v[174:175], off
	v_lshl_add_u64 v[174:175], s[4:5], 0, v[198:199]
	s_mov_b32 m0, s67
	s_nop 0
	global_load_lds_dwordx4 v[174:175], off
	s_waitcnt lgkmcnt(8)
	s_waitcnt lgkmcnt(0)
	v_mfma_f32_16x16x32_bf16 v[154:157], v[106:109], v[126:129], v[154:157]
	v_mfma_f32_16x16x32_bf16 v[190:193], v[110:113], v[130:133], v[154:157]
	v_mfma_f32_16x16x32_bf16 v[154:157], v[114:117], v[126:129], v[158:161]
	v_mfma_f32_16x16x32_bf16 v[186:189], v[118:121], v[130:133], v[154:157]
	s_barrier
	s_waitcnt lgkmcnt(0)
	s_setprio 1
	s_waitcnt lgkmcnt(0)
	v_mfma_f32_16x16x32_bf16 v[154:157], v[106:109], v[134:137], v[166:169]
	v_mfma_f32_16x16x32_bf16 v[174:177], v[110:113], v[138:141], v[154:157]
	v_mfma_f32_16x16x32_bf16 v[154:157], v[114:117], v[134:137], v[162:165]
	v_mfma_f32_16x16x32_bf16 v[94:97], v[106:109], v[142:145], v[94:97]
	v_mfma_f32_16x16x32_bf16 v[90:93], v[114:117], v[142:145], v[90:93]
	v_mfma_f32_16x16x32_bf16 v[78:81], v[106:109], v[150:153], v[78:81]
	v_mfma_f32_16x16x32_bf16 v[74:77], v[114:117], v[150:153], v[74:77]
	v_mfma_f32_16x16x32_bf16 v[162:165], v[118:121], v[138:141], v[154:157]
	v_mfma_f32_16x16x32_bf16 v[94:97], v[110:113], v[146:149], v[94:97]
	v_mfma_f32_16x16x32_bf16 v[90:93], v[118:121], v[146:149], v[90:93]
	v_mfma_f32_16x16x32_bf16 v[78:81], v[110:113], v[170:173], v[78:81]
	v_mfma_f32_16x16x32_bf16 v[74:77], v[118:121], v[170:173], v[74:77]
	s_setprio 0
	s_barrier
	s_add_i32 s4, 0, 0x1c000
	v_add_u32_e32 v178, s4, v217
	s_add_i32 s5, s8, s43
	ds_read_b128 v[154:157], v178
	ds_read_b128 v[158:161], v178 offset:1024
	ds_read_b128 v[166:169], v178 offset:2048
	ds_read_b128 v[206:209], v178 offset:3072
	v_lshl_add_u64 v[178:179], v[210:211], 0, s[60:61]
	s_mov_b32 m0, s5
	s_nop 0
	global_load_lds_dwordx4 v[178:179], off
	v_lshl_add_u64 v[178:179], v[212:213], 0, s[60:61]
	s_add_i32 m0, s5, 0x2000
	s_nop 0
	global_load_lds_dwordx4 v[178:179], off
	s_waitcnt lgkmcnt(0)
	v_mfma_f32_16x16x32_bf16 v[178:181], v[154:157], v[126:129], v[182:185]
	v_mfma_f32_16x16x32_bf16 v[122:125], v[166:169], v[126:129], v[122:125]
	v_mfma_f32_16x16x32_bf16 v[102:105], v[154:157], v[134:137], v[102:105]
	v_mfma_f32_16x16x32_bf16 v[98:101], v[166:169], v[134:137], v[98:101]
	s_barrier
; #define PG8_STAGE(bufoff, gbase, voff) do { _Pragma("unroll") for (int _i = 0; _i < 2; ++_i) \
;         __builtin_amdgcn_global_load_lds((const unsigned*)((const char*)(gbase) + (voff)[_i]), (LAS unsigned*)(lds + (bufoff) + ldsw + _i * 8192), 16, 0, 0); } while (0)
; #define PG8_LDA(dst, b, h) do { _Pragma("unroll") for (int m = 0; m < 4; ++m) _Pragma("unroll") for (int k = 0; k < 2; ++k) dst[m][k] = *(const LAS bf16x8*)(lds + PG8_SA(b, h) + aoff + m * 2048 + k * 1024); } while (0)
; #define PG8_MMA(ai, bj, At, Bt) do { __builtin_amdgcn_s_setprio(1); _Pragma("unroll") for (int m = 0; m < 4; ++m) _Pragma("unroll") for (int n = 0; n < 2; ++n) _Pragma("unroll") for (int k = 0; k < 2; ++k) \
;         acc[ai][bj][m][n] = __builtin_amdgcn_mfma_f32_16x16x32_bf16(Bt[n][k], At[m][k], acc[ai][bj][m][n], 0, 0, 0); __builtin_amdgcn_s_setprio(0); } while (0)
; #define PG8_WAIT_V(n) asm volatile("s_waitcnt vmcnt(" #n ")" ::: "memory")
; #define PG8_WAIT_L(n) asm volatile("s_waitcnt lgkmcnt(" #n ")" ::: "memory")
; #define PG8_BAR __builtin_amdgcn_s_barrier()
; #define PG8_SCHED __builtin_amdgcn_sched_barrier(0)
; template <class Epi>
; __device__ __forceinline__ void gemm_phase(LAS unsigned char* lds, const Gemm g, const Sched& S, const Epi& E) {
;     ...
;             PG8_BAR; PG8_WAIT_L(0); PG8_MMA(0, 1, At, B1); PG8_BAR;
;             PG8_LDA(At, 1, 1); PG8_STAGE(PG8_SA(1, 0), a3, voffA);
;             PG8_BAR; PG8_WAIT_L(0); PG8_MMA(1, 0, At, B0); PG8_BAR; PG8_SCHED;
;             PG8_STAGE(PG8_SB(1, 1), b3 + hstepB, voffB);
;             PG8_WAIT_V(6); PG8_BAR; PG8_MMA(1, 1, At, B1); PG8_BAR;
;         }
;     __device__ __forceinline__ void operator()(const Acc& acc, const Unit& u, int wr, int wc, int fr, int fq, const Pre& pre) const {
;         const int row0 = u.pm * 256 + wr * 64 + fr, col0 = u.pn * 256 + wc * 32 + 8 * fq;
;         const size_t zo = (size_t)(u.zb * sOb + u.zh * sOh);
	s_waitcnt lgkmcnt(0)
	s_setprio 1
	s_waitcnt lgkmcnt(0)
	v_mfma_f32_16x16x32_bf16 v[86:89], v[154:157], v[142:145], v[86:89]
	v_mfma_f32_16x16x32_bf16 v[82:85], v[166:169], v[142:145], v[82:85]
	v_mfma_f32_16x16x32_bf16 v[70:73], v[154:157], v[150:153], v[70:73]
	v_mfma_f32_16x16x32_bf16 v[66:69], v[166:169], v[150:153], v[66:69]
	v_mfma_f32_16x16x32_bf16 v[182:185], v[158:161], v[130:133], v[178:181]
	v_mfma_f32_16x16x32_bf16 v[178:181], v[206:209], v[130:133], v[122:125]
	v_mfma_f32_16x16x32_bf16 v[102:105], v[158:161], v[138:141], v[102:105]
	v_mfma_f32_16x16x32_bf16 v[98:101], v[206:209], v[138:141], v[98:101]
	v_mfma_f32_16x16x32_bf16 v[86:89], v[158:161], v[146:149], v[86:89]
	v_mfma_f32_16x16x32_bf16 v[82:85], v[206:209], v[146:149], v[82:85]
	v_mfma_f32_16x16x32_bf16 v[70:73], v[158:161], v[170:173], v[70:73]
	v_mfma_f32_16x16x32_bf16 v[66:69], v[206:209], v[170:173], v[66:69]
	s_setprio 0
	s_mov_b32 m0, s51
	v_lshl_add_u64 v[170:171], v[214:215], 0, s[60:61]
	s_barrier
	ds_read_b128 v[122:125], v235 offset:49152
	ds_read_b128 v[126:129], v235 offset:50176
	ds_read_b128 v[130:133], v235 offset:51200
	ds_read_b128 v[134:137], v235 offset:52224
	ds_read_b128 v[138:141], v235 offset:53248
	ds_read_b128 v[142:145], v235 offset:54272
	ds_read_b128 v[146:149], v235 offset:55296
	ds_read_b128 v[150:153], v235 offset:56320
	global_load_lds_dwordx4 v[170:171], off
	v_lshl_add_u64 v[170:171], v[222:223], 0, s[60:61]
	s_mov_b32 m0, s2
	s_nop 0
	global_load_lds_dwordx4 v[170:171], off
	s_add_i32 s4, s4, s43
	v_lshl_add_u64 v[170:171], v[224:225], 0, s[60:61]
	s_mov_b32 m0, s4
	s_nop 0
	global_load_lds_dwordx4 v[170:171], off
	v_lshl_add_u64 v[170:171], v[226:227], 0, s[60:61]
	s_add_i32 m0, s4, 0x2000
	s_nop 0
	global_load_lds_dwordx4 v[170:171], off
	s_waitcnt vmcnt(6)
	s_waitcnt lgkmcnt(0)
	v_mfma_f32_16x16x32_bf16 v[62:65], v[106:109], v[122:125], v[62:65]
	v_mfma_f32_16x16x32_bf16 v[58:61], v[114:117], v[122:125], v[58:61]
	v_mfma_f32_16x16x32_bf16 v[46:49], v[106:109], v[130:133], v[46:49]
	v_mfma_f32_16x16x32_bf16 v[42:45], v[114:117], v[130:133], v[42:45]
	s_barrier
	s_setprio 1
	v_mfma_f32_16x16x32_bf16 v[30:33], v[106:109], v[138:141], v[30:33]
	v_mfma_f32_16x16x32_bf16 v[26:29], v[114:117], v[138:141], v[26:29]
	v_mfma_f32_16x16x32_bf16 v[14:17], v[106:109], v[146:149], v[14:17]
	v_mfma_f32_16x16x32_bf16 v[10:13], v[114:117], v[146:149], v[10:13]
	v_mfma_f32_16x16x32_bf16 v[62:65], v[110:113], v[126:129], v[62:65]
	v_mfma_f32_16x16x32_bf16 v[58:61], v[118:121], v[126:129], v[58:61]
	v_mfma_f32_16x16x32_bf16 v[46:49], v[110:113], v[134:137], v[46:49]
	v_mfma_f32_16x16x32_bf16 v[42:45], v[118:121], v[134:137], v[42:45]
	v_mfma_f32_16x16x32_bf16 v[30:33], v[110:113], v[142:145], v[30:33]
	v_mfma_f32_16x16x32_bf16 v[26:29], v[118:121], v[142:145], v[26:29]
	v_mfma_f32_16x16x32_bf16 v[14:17], v[110:113], v[150:153], v[14:17]
	v_mfma_f32_16x16x32_bf16 v[10:13], v[118:121], v[150:153], v[10:13]
	v_mfma_f32_16x16x32_bf16 v[54:57], v[154:157], v[122:125], v[54:57]
	v_mfma_f32_16x16x32_bf16 v[50:53], v[166:169], v[122:125], v[50:53]
	v_mfma_f32_16x16x32_bf16 v[38:41], v[154:157], v[130:133], v[38:41]
	v_mfma_f32_16x16x32_bf16 v[34:37], v[166:169], v[130:133], v[34:37]
	v_mfma_f32_16x16x32_bf16 v[22:25], v[154:157], v[138:141], v[22:25]
	v_mfma_f32_16x16x32_bf16 v[18:21], v[166:169], v[138:141], v[18:21]
	v_mfma_f32_16x16x32_bf16 v[6:9], v[154:157], v[146:149], v[6:9]
	v_mfma_f32_16x16x32_bf16 v[2:5], v[166:169], v[146:149], v[2:5]
	v_mfma_f32_16x16x32_bf16 v[54:57], v[158:161], v[126:129], v[54:57]
	v_mfma_f32_16x16x32_bf16 v[50:53], v[206:209], v[126:129], v[50:53]
	v_mfma_f32_16x16x32_bf16 v[38:41], v[158:161], v[134:137], v[38:41]
	v_mfma_f32_16x16x32_bf16 v[34:37], v[206:209], v[134:137], v[34:37]
	v_mfma_f32_16x16x32_bf16 v[22:25], v[158:161], v[142:145], v[22:25]
	v_mfma_f32_16x16x32_bf16 v[18:21], v[206:209], v[142:145], v[18:21]
	v_mfma_f32_16x16x32_bf16 v[6:9], v[158:161], v[150:153], v[6:9]
	v_mfma_f32_16x16x32_bf16 v[2:5], v[206:209], v[150:153], v[2:5]
	s_setprio 0
	s_add_u32 s0, s0, 0x100
	s_addc_u32 s1, s1, 0
	s_add_u32 s34, s34, 0x100
	s_addc_u32 s35, s35, 0
	s_cmp_ge_u32 s14, s73
	s_mov_b32 s4, s14
	s_barrier
	s_cbranch_scc0 .LBB0_719
	s_ashr_i32 s0, s42, 31
	s_ashr_i32 s4, s24, 31
	v_readlane_b32 s8, v253, 59
	s_mul_hi_u32 s1, s74, s42
	s_mul_i32 s0, s74, s0
	v_readlane_b32 s9, v253, 60
	s_mul_hi_u32 s5, s8, s24
	s_mul_i32 s4, s8, s4
	s_add_i32 s0, s1, s0
	s_mul_i32 s1, s75, s42
	s_add_i32 s4, s5, s4
	s_mul_i32 s5, s9, s24
	v_lshl_add_u32 v206, s97, 8, v216
	s_add_i32 s0, s0, s1
	s_mul_i32 s1, s74, s42
	s_add_i32 s4, s4, s5
	s_mul_i32 s5, s8, s24
	v_lshl_or_b32 v210, s96, 8, v234
	s_add_u32 s94, s1, s5
	v_ashrrev_i32_e32 v207, 31, v206
	s_addc_u32 s95, s0, s4
	v_ashrrev_i32_e32 v211, 31, v210
	s_mov_b64 s[0:1], -1
	v_readfirstlane_b32 s98, v219
	s_nop 1
	s_bitcmp1_b32 s98, 8
	s_cbranch_scc1 .Lresync_x_719_p
	s_barrier
	s_branch .Lresync_x_719

;     __device__ __forceinline__ void operator()(const Acc& acc, const Unit& u, int wr, int wc, int fr, int fq, const Pre& pre) const {
;     ...
;             if (base) {
; #pragma unroll
;                 for (int m = 0; m < 4; ++m) { const size_t off = zo + (size_t)(row0 + ai * 128 + m * 16) * ldc + col0;
; #pragma unroll
;                     for (int bj = 0; bj < 2; ++bj)
; #pragma unroll
;                         for (int n = 0; n < 2; ++n) bv[m][bj][n] = *(const f32x4*)(base + off + bj * 128 + n * 4); }
.Lresync_x_719:
	s_and_b64 vcc, exec, s[78:79]
	v_mul_lo_u32 v208, s13, v206
	v_mul_lo_u32 v236, s12, v207
	v_or_b32_e32 v239, 16, v206
	v_or_b32_e32 v238, 32, v206
	v_or_b32_e32 v237, 48, v206
	s_cbranch_vccz .LBB0_722
	s_lshl_b64 s[0:1], s[94:95], 2
	v_readlane_b32 s4, v254, 7
	v_readlane_b32 s5, v254, 8
	s_add_u32 s0, s4, s0
	s_addc_u32 s1, s5, s1
	v_lshl_add_u64 v[154:155], v[210:211], 2, s[0:1]
	v_mad_u64_u32 v[212:213], s[0:1], s12, v206, 0
	v_mul_lo_u32 v124, s13, v239
	v_mad_u64_u32 v[122:123], s[0:1], s12, v239, 0
	v_mul_lo_u32 v140, s13, v238
	v_mad_u64_u32 v[138:139], s[0:1], s12, v238, 0
	v_mul_lo_u32 v158, s13, v237
	v_mad_u64_u32 v[156:157], s[0:1], s12, v237, 0
	v_add3_u32 v213, v213, v236, v208
	v_add3_u32 v123, v123, v236, v124
	v_add3_u32 v139, v139, v236, v140
	v_add3_u32 v157, v157, v236, v158
	v_lshl_add_u64 v[118:119], v[212:213], 2, v[154:155]
	v_lshl_add_u64 v[134:135], v[122:123], 2, v[154:155]
	v_lshl_add_u64 v[150:151], v[138:139], 2, v[154:155]
	v_lshl_add_u64 v[170:171], v[156:157], 2, v[154:155]
	flat_load_dwordx4 v[106:109], v[118:119] nt
	flat_load_dwordx4 v[110:113], v[118:119] offset:16 nt
	flat_load_dwordx4 v[114:117], v[118:119] offset:512 nt
	s_nop 0
	flat_load_dwordx4 v[118:121], v[118:119] offset:528 nt
	s_nop 0
	flat_load_dwordx4 v[122:125], v[134:135] nt
	flat_load_dwordx4 v[126:129], v[134:135] offset:16 nt
	flat_load_dwordx4 v[130:133], v[134:135] offset:512 nt
	s_nop 0
	flat_load_dwordx4 v[134:137], v[134:135] offset:528 nt
	s_nop 0
	flat_load_dwordx4 v[138:141], v[150:151] nt
	flat_load_dwordx4 v[142:145], v[150:151] offset:16 nt
	flat_load_dwordx4 v[146:149], v[150:151] offset:512 nt
	s_nop 0
	flat_load_dwordx4 v[150:153], v[150:151] offset:528 nt
	s_nop 0
	flat_load_dwordx4 v[154:157], v[170:171] nt
	flat_load_dwordx4 v[158:161], v[170:171] offset:16 nt
	flat_load_dwordx4 v[166:169], v[170:171] offset:512 nt
	s_nop 0
	flat_load_dwordx4 v[170:173], v[170:171] offset:528 nt
	s_mov_b64 s[0:1], 0

; #define PG8_STAGE(bufoff, gbase, voff) do { _Pragma("unroll") for (int _i = 0; _i < 2; ++_i) \
;         __builtin_amdgcn_global_load_lds((const unsigned*)((const char*)(gbase) + (voff)[_i]), (LAS unsigned*)(lds + (bufoff) + ldsw + _i * 8192), 16, 0, 0); } while (0)
; #define PG8_LDA(dst, b, h) do { _Pragma("unroll") for (int m = 0; m < 4; ++m) _Pragma("unroll") for (int k = 0; k < 2; ++k) dst[m][k] = *(const LAS bf16x8*)(lds + PG8_SA(b, h) + aoff + m * 2048 + k * 1024); } while (0)
; #define PG8_LDB(dst, b, h) do { _Pragma("unroll") for (int n = 0; n < 2; ++n) _Pragma("unroll") for (int k = 0; k < 2; ++k) dst[n][k] = *(const LAS bf16x8*)(lds + PG8_SB(b, h) + boff + n * 2048 + k * 1024); } while (0)
; #define PG8_MMA(ai, bj, At, Bt) do { __builtin_amdgcn_s_setprio(1); _Pragma("unroll") for (int m = 0; m < 4; ++m) _Pragma("unroll") for (int n = 0; n < 2; ++n) _Pragma("unroll") for (int k = 0; k < 2; ++k) \
;         acc[ai][bj][m][n] = __builtin_amdgcn_mfma_f32_16x16x32_bf16(Bt[n][k], At[m][k], acc[ai][bj][m][n], 0, 0, 0); __builtin_amdgcn_s_setprio(0); } while (0)
; #define PG8_WAIT_V(n) asm volatile("s_waitcnt vmcnt(" #n ")" ::: "memory")
; #define PG8_WAIT_L(n) asm volatile("s_waitcnt lgkmcnt(" #n ")" ::: "memory")
; template <class Epi>
; __device__ __forceinline__ void gemm_phase(LAS unsigned char* lds, const Gemm g, const Sched& S, const Epi& E) {
;     ...
;         for (int t = 0; t < nt; t += 2) {
;             const bool last = (t == nt - 2);
;             const char* a1 = cA + (size_t)(t + 1) * kstep;
;             const char* a2 = last ? nA : cA + (size_t)(t + 2) * kstep; const char* b2 = last ? nB : cB + (size_t)(t + 2) * kstep;
;             const char* a3 = a2 + kstep; const char* b3 = b2 + kstep;
;             PG8_LDB(B0, 0, 0); PG8_SCHED; PG8_LDA(At, 0, 0); PG8_STAGE(PG8_SA(1, 1), a1 + hstepA, voffA);
;             PG8_WAIT_L(8); PG8_BAR; PG8_WAIT_L(0); PG8_MMA(0, 0, At, B0); PG8_BAR; PG8_SCHED;
;             PG8_LDB(B1, 0, 1); PG8_STAGE(PG8_SB(0, 0), b2, voffB);
;             PG8_BAR; PG8_WAIT_L(0); PG8_MMA(0, 1, At, B1); PG8_BAR;
;             PG8_LDA(At, 0, 1); PG8_STAGE(PG8_SA(0, 0), a2, voffA);
;             PG8_BAR; PG8_WAIT_L(0); PG8_MMA(1, 0, At, B0); PG8_BAR; PG8_SCHED;
;             PG8_STAGE(PG8_SB(0, 1), b2 + hstepB, voffB);
;             PG8_WAIT_V(6); PG8_BAR; PG8_MMA(1, 1, At, B1); PG8_BAR;
.Lresync_y_825:
.LBB0_825:
	s_add_i32 s86, s68, 2
	s_add_u32 s70, s4, 0x80
	s_addc_u32 s69, s5, 0
	s_add_i32 s87, 0, 0x10000
	v_add_u32_e32 v144, s87, v145
	ds_read_b128 v[152:155], v144
	ds_read_b128 v[156:159], v144 offset:1024
	ds_read_b128 v[160:163], v144 offset:2048
	ds_read_b128 v[164:167], v144 offset:3072
	s_cmp_eq_u32 s77, s68
	s_cselect_b32 s68, s59, s70
	s_cselect_b32 s69, s57, s69
	s_cselect_b32 s71, s82, s85
	s_cselect_b32 s70, s83, s84
	v_lshl_add_u64 v[192:193], s[4:5], 0, v[136:137]
	s_add_i32 m0, s33, 0xc000
	ds_read_b128 v[168:171], v151
	ds_read_b128 v[172:175], v151 offset:1024
	ds_read_b128 v[176:179], v151 offset:2048
	ds_read_b128 v[180:183], v151 offset:3072
	ds_read_b128 v[184:187], v151 offset:4096
	ds_read_b128 v[188:191], v151 offset:5120
	ds_read_b128 v[196:199], v151 offset:6144
	ds_read_b128 v[200:203], v151 offset:7168
	global_load_lds_dwordx4 v[192:193], off
	v_lshl_add_u64 v[192:193], s[4:5], 0, v[138:139]
	s_add_i32 m0, s33, 0xe000
	s_nop 0
	global_load_lds_dwordx4 v[192:193], off
	s_add_i32 s88, 0, 0x14000
	v_add_u32_e32 v144, s88, v145
	ds_read_b128 v[204:207], v144
	ds_read_b128 v[208:211], v144 offset:1024
	ds_read_b128 v[212:215], v144 offset:2048
	ds_read_b128 v[234:237], v144 offset:3072
	s_waitcnt vmcnt(8)
	s_waitcnt lgkmcnt(0)
	v_mfma_f32_16x16x32_bf16 v[126:129], v[152:155], v[168:171], v[126:129]
	v_mfma_f32_16x16x32_bf16 v[122:125], v[160:163], v[168:171], v[122:125]
	v_mfma_f32_16x16x32_bf16 v[110:113], v[152:155], v[176:179], v[110:113]
	v_mfma_f32_16x16x32_bf16 v[106:109], v[160:163], v[176:179], v[106:109]
	s_barrier
	s_setprio 1
	v_mfma_f32_16x16x32_bf16 v[94:97], v[152:155], v[184:187], v[94:97]
	v_mfma_f32_16x16x32_bf16 v[90:93], v[160:163], v[184:187], v[90:93]
	v_mfma_f32_16x16x32_bf16 v[78:81], v[152:155], v[196:199], v[78:81]
	v_mfma_f32_16x16x32_bf16 v[74:77], v[160:163], v[196:199], v[74:77]
	v_mfma_f32_16x16x32_bf16 v[126:129], v[156:159], v[172:175], v[126:129]
	v_mfma_f32_16x16x32_bf16 v[122:125], v[164:167], v[172:175], v[122:125]
	v_mfma_f32_16x16x32_bf16 v[110:113], v[156:159], v[180:183], v[110:113]
	v_mfma_f32_16x16x32_bf16 v[106:109], v[164:167], v[180:183], v[106:109]
	v_mfma_f32_16x16x32_bf16 v[94:97], v[156:159], v[188:191], v[94:97]
	v_mfma_f32_16x16x32_bf16 v[90:93], v[164:167], v[188:191], v[90:93]
	v_mfma_f32_16x16x32_bf16 v[78:81], v[156:159], v[200:203], v[78:81]
	v_mfma_f32_16x16x32_bf16 v[74:77], v[164:167], v[200:203], v[74:77]
	v_mfma_f32_16x16x32_bf16 v[118:121], v[204:207], v[168:171], v[118:121]
	v_mfma_f32_16x16x32_bf16 v[114:117], v[212:215], v[168:171], v[114:117]
	v_mfma_f32_16x16x32_bf16 v[102:105], v[204:207], v[176:179], v[102:105]
	v_mfma_f32_16x16x32_bf16 v[98:101], v[212:215], v[176:179], v[98:101]
	v_mfma_f32_16x16x32_bf16 v[86:89], v[204:207], v[184:187], v[86:89]
	v_mfma_f32_16x16x32_bf16 v[82:85], v[212:215], v[184:187], v[82:85]
	v_mfma_f32_16x16x32_bf16 v[70:73], v[204:207], v[196:199], v[70:73]
	v_mfma_f32_16x16x32_bf16 v[66:69], v[212:215], v[196:199], v[66:69]
	v_mfma_f32_16x16x32_bf16 v[118:121], v[208:211], v[172:175], v[118:121]
	v_mfma_f32_16x16x32_bf16 v[114:117], v[234:237], v[172:175], v[114:117]
	v_mfma_f32_16x16x32_bf16 v[102:105], v[208:211], v[180:183], v[102:105]
	v_mfma_f32_16x16x32_bf16 v[98:101], v[234:237], v[180:183], v[98:101]
	v_mfma_f32_16x16x32_bf16 v[86:89], v[208:211], v[188:191], v[86:89]
	v_mfma_f32_16x16x32_bf16 v[82:85], v[234:237], v[188:191], v[82:85]
	v_mfma_f32_16x16x32_bf16 v[70:73], v[208:211], v[200:203], v[70:73]
	v_mfma_f32_16x16x32_bf16 v[66:69], v[234:237], v[200:203], v[66:69]
	s_setprio 0
	s_barrier
	s_add_i32 s87, s87, s51
	v_lshl_add_u64 v[192:193], s[70:71], 0, v[0:1]
	s_mov_b32 m0, s87
	s_nop 0
	global_load_lds_dwordx4 v[192:193], off
	v_lshl_add_u64 v[216:217], s[70:71], 0, v[134:135]
	s_add_i32 m0, s87, 0x2000
	s_nop 0
	global_load_lds_dwordx4 v[216:217], off
	s_mov_b32 m0, s33
	v_lshl_add_u64 v[222:223], s[68:69], 0, v[130:131]
	ds_read_b128 v[168:171], v151 offset:16384
	ds_read_b128 v[172:175], v151 offset:17408
	ds_read_b128 v[176:179], v151 offset:18432
	ds_read_b128 v[180:183], v151 offset:19456
	ds_read_b128 v[184:187], v151 offset:20480
	ds_read_b128 v[188:191], v151 offset:21504
	ds_read_b128 v[196:199], v151 offset:22528
	ds_read_b128 v[200:203], v151 offset:23552
	global_load_lds_dwordx4 v[222:223], off
	v_lshl_add_u64 v[224:225], s[68:69], 0, v[132:133]
	s_mov_b32 m0, s48
	s_nop 0
	global_load_lds_dwordx4 v[224:225], off
	s_add_u32 s70, s70, s14
	s_addc_u32 s71, s71, s15
	s_add_i32 s87, s88, s51
	v_lshl_add_u64 v[226:227], s[70:71], 0, v[0:1]
	s_mov_b32 m0, s87
	v_lshl_add_u64 v[228:229], s[70:71], 0, v[134:135]
	global_load_lds_dwordx4 v[226:227], off
	s_add_i32 m0, s87, 0x2000
	s_nop 0
	global_load_lds_dwordx4 v[228:229], off
	s_waitcnt vmcnt(8)
	s_waitcnt lgkmcnt(0)
	v_mfma_f32_16x16x32_bf16 v[62:65], v[152:155], v[168:171], v[62:65]
	v_mfma_f32_16x16x32_bf16 v[58:61], v[160:163], v[168:171], v[58:61]
	v_mfma_f32_16x16x32_bf16 v[46:49], v[152:155], v[176:179], v[46:49]
	v_mfma_f32_16x16x32_bf16 v[42:45], v[160:163], v[176:179], v[42:45]
	s_barrier
; #define PG8_STAGE(bufoff, gbase, voff) do { _Pragma("unroll") for (int _i = 0; _i < 2; ++_i) \
;         __builtin_amdgcn_global_load_lds((const unsigned*)((const char*)(gbase) + (voff)[_i]), (LAS unsigned*)(lds + (bufoff) + ldsw + _i * 8192), 16, 0, 0); } while (0)
; #define PG8_LDA(dst, b, h) do { _Pragma("unroll") for (int m = 0; m < 4; ++m) _Pragma("unroll") for (int k = 0; k < 2; ++k) dst[m][k] = *(const LAS bf16x8*)(lds + PG8_SA(b, h) + aoff + m * 2048 + k * 1024); } while (0)
; #define PG8_LDB(dst, b, h) do { _Pragma("unroll") for (int n = 0; n < 2; ++n) _Pragma("unroll") for (int k = 0; k < 2; ++k) dst[n][k] = *(const LAS bf16x8*)(lds + PG8_SB(b, h) + boff + n * 2048 + k * 1024); } while (0)
; #define PG8_MMA(ai, bj, At, Bt) do { __builtin_amdgcn_s_setprio(1); _Pragma("unroll") for (int m = 0; m < 4; ++m) _Pragma("unroll") for (int n = 0; n < 2; ++n) _Pragma("unroll") for (int k = 0; k < 2; ++k) \
;         acc[ai][bj][m][n] = __builtin_amdgcn_mfma_f32_16x16x32_bf16(Bt[n][k], At[m][k], acc[ai][bj][m][n], 0, 0, 0); __builtin_amdgcn_s_setprio(0); } while (0)
; #define PG8_WAIT_V(n) asm volatile("s_waitcnt vmcnt(" #n ")" ::: "memory")
; #define PG8_WAIT_L(n) asm volatile("s_waitcnt lgkmcnt(" #n ")" ::: "memory")
; #define PG8_BAR __builtin_amdgcn_s_barrier()
; #define PG8_SCHED __builtin_amdgcn_sched_barrier(0)
; template <class Epi>
; __device__ __forceinline__ void gemm_phase(LAS unsigned char* lds, const Gemm g, const Sched& S, const Epi& E) {
;     ...
;             PG8_WAIT_V(6); PG8_BAR; PG8_MMA(1, 1, At, B1); PG8_BAR;
;             PG8_LDB(B0, 1, 0); PG8_SCHED; PG8_LDA(At, 1, 0); PG8_STAGE(PG8_SA(0, 1), a2 + hstepA, voffA);
;             PG8_WAIT_L(8); PG8_BAR; PG8_WAIT_L(0); PG8_MMA(0, 0, At, B0); PG8_BAR; PG8_SCHED;
;             PG8_LDB(B1, 1, 1); PG8_STAGE(PG8_SB(1, 0), b3, voffB);
;             PG8_BAR; PG8_WAIT_L(0); PG8_MMA(0, 1, At, B1); PG8_BAR;
	s_setprio 1
	v_mfma_f32_16x16x32_bf16 v[30:33], v[152:155], v[184:187], v[30:33]
	v_mfma_f32_16x16x32_bf16 v[26:29], v[160:163], v[184:187], v[26:29]
	v_mfma_f32_16x16x32_bf16 v[14:17], v[152:155], v[196:199], v[14:17]
	v_mfma_f32_16x16x32_bf16 v[10:13], v[160:163], v[196:199], v[10:13]
	v_mfma_f32_16x16x32_bf16 v[62:65], v[156:159], v[172:175], v[62:65]
	v_mfma_f32_16x16x32_bf16 v[58:61], v[164:167], v[172:175], v[58:61]
	v_mfma_f32_16x16x32_bf16 v[46:49], v[156:159], v[180:183], v[46:49]
	v_mfma_f32_16x16x32_bf16 v[42:45], v[164:167], v[180:183], v[42:45]
	v_mfma_f32_16x16x32_bf16 v[30:33], v[156:159], v[188:191], v[30:33]
	v_mfma_f32_16x16x32_bf16 v[26:29], v[164:167], v[188:191], v[26:29]
	v_mfma_f32_16x16x32_bf16 v[14:17], v[156:159], v[200:203], v[14:17]
	v_mfma_f32_16x16x32_bf16 v[10:13], v[164:167], v[200:203], v[10:13]
	v_mfma_f32_16x16x32_bf16 v[54:57], v[204:207], v[168:171], v[54:57]
	v_mfma_f32_16x16x32_bf16 v[50:53], v[212:215], v[168:171], v[50:53]
	v_mfma_f32_16x16x32_bf16 v[38:41], v[204:207], v[176:179], v[38:41]
	v_mfma_f32_16x16x32_bf16 v[34:37], v[212:215], v[176:179], v[34:37]
	v_mfma_f32_16x16x32_bf16 v[22:25], v[204:207], v[184:187], v[22:25]
	v_mfma_f32_16x16x32_bf16 v[18:21], v[212:215], v[184:187], v[18:21]
	v_mfma_f32_16x16x32_bf16 v[6:9], v[204:207], v[196:199], v[6:9]
	v_mfma_f32_16x16x32_bf16 v[2:5], v[212:215], v[196:199], v[2:5]
	v_mfma_f32_16x16x32_bf16 v[54:57], v[208:211], v[172:175], v[54:57]
	v_mfma_f32_16x16x32_bf16 v[50:53], v[234:237], v[172:175], v[50:53]
	v_mfma_f32_16x16x32_bf16 v[38:41], v[208:211], v[180:183], v[38:41]
	v_mfma_f32_16x16x32_bf16 v[34:37], v[234:237], v[180:183], v[34:37]
	v_mfma_f32_16x16x32_bf16 v[22:25], v[208:211], v[188:191], v[22:25]
	v_mfma_f32_16x16x32_bf16 v[18:21], v[234:237], v[188:191], v[18:21]
	v_mfma_f32_16x16x32_bf16 v[6:9], v[208:211], v[200:203], v[6:9]
	v_mfma_f32_16x16x32_bf16 v[2:5], v[234:237], v[200:203], v[2:5]
	s_setprio 0
	s_barrier
	s_add_i32 s70, 0, 0x18000
	v_add_u32_e32 v144, s70, v145
	ds_read_b128 v[152:155], v144
	ds_read_b128 v[156:159], v144 offset:1024
	ds_read_b128 v[160:163], v144 offset:2048
	ds_read_b128 v[164:167], v144 offset:3072
	s_add_u32 s68, s68, s6
	s_addc_u32 s69, s69, s7
	s_mov_b32 m0, s58
	v_lshl_add_u64 v[204:205], s[68:69], 0, v[130:131]
	ds_read_b128 v[168:171], v151 offset:32768
	ds_read_b128 v[172:175], v151 offset:33792
	ds_read_b128 v[176:179], v151 offset:34816
	ds_read_b128 v[180:183], v151 offset:35840
	ds_read_b128 v[184:187], v151 offset:36864
	ds_read_b128 v[188:191], v151 offset:37888
	ds_read_b128 v[196:199], v151 offset:38912
	ds_read_b128 v[200:203], v151 offset:39936
	global_load_lds_dwordx4 v[204:205], off
	v_lshl_add_u64 v[204:205], s[68:69], 0, v[132:133]
	s_mov_b32 m0, s72
	s_nop 0
	global_load_lds_dwordx4 v[204:205], off
	s_add_i32 s68, 0, 0x1c000
	v_add_u32_e32 v144, s68, v145
	ds_read_b128 v[204:207], v144
	ds_read_b128 v[208:211], v144 offset:1024
	ds_read_b128 v[212:215], v144 offset:2048
	ds_read_b128 v[234:237], v144 offset:3072
	s_waitcnt vmcnt(8)
	s_waitcnt lgkmcnt(0)
	v_mfma_f32_16x16x32_bf16 v[126:129], v[152:155], v[168:171], v[126:129]
	v_mfma_f32_16x16x32_bf16 v[122:125], v[160:163], v[168:171], v[122:125]
	v_mfma_f32_16x16x32_bf16 v[110:113], v[152:155], v[176:179], v[110:113]
	v_mfma_f32_16x16x32_bf16 v[106:109], v[160:163], v[176:179], v[106:109]
	s_barrier
	s_setprio 1
	v_mfma_f32_16x16x32_bf16 v[94:97], v[152:155], v[184:187], v[94:97]
	v_mfma_f32_16x16x32_bf16 v[90:93], v[160:163], v[184:187], v[90:93]
	v_mfma_f32_16x16x32_bf16 v[78:81], v[152:155], v[196:199], v[78:81]
	v_mfma_f32_16x16x32_bf16 v[74:77], v[160:163], v[196:199], v[74:77]
	v_mfma_f32_16x16x32_bf16 v[126:129], v[156:159], v[172:175], v[126:129]
	v_mfma_f32_16x16x32_bf16 v[122:125], v[164:167], v[172:175], v[122:125]
	v_mfma_f32_16x16x32_bf16 v[110:113], v[156:159], v[180:183], v[110:113]
	v_mfma_f32_16x16x32_bf16 v[106:109], v[164:167], v[180:183], v[106:109]
	v_mfma_f32_16x16x32_bf16 v[94:97], v[156:159], v[188:191], v[94:97]
	v_mfma_f32_16x16x32_bf16 v[90:93], v[164:167], v[188:191], v[90:93]
	v_mfma_f32_16x16x32_bf16 v[78:81], v[156:159], v[200:203], v[78:81]
	v_mfma_f32_16x16x32_bf16 v[74:77], v[164:167], v[200:203], v[74:77]
	v_mfma_f32_16x16x32_bf16 v[118:121], v[204:207], v[168:171], v[118:121]
	v_mfma_f32_16x16x32_bf16 v[114:117], v[212:215], v[168:171], v[114:117]
	v_mfma_f32_16x16x32_bf16 v[102:105], v[204:207], v[176:179], v[102:105]
	v_mfma_f32_16x16x32_bf16 v[98:101], v[212:215], v[176:179], v[98:101]
	v_mfma_f32_16x16x32_bf16 v[86:89], v[204:207], v[184:187], v[86:89]
	v_mfma_f32_16x16x32_bf16 v[82:85], v[212:215], v[184:187], v[82:85]
	v_mfma_f32_16x16x32_bf16 v[70:73], v[204:207], v[196:199], v[70:73]
	v_mfma_f32_16x16x32_bf16 v[66:69], v[212:215], v[196:199], v[66:69]
	v_mfma_f32_16x16x32_bf16 v[118:121], v[208:211], v[172:175], v[118:121]
	v_mfma_f32_16x16x32_bf16 v[114:117], v[234:237], v[172:175], v[114:117]
	v_mfma_f32_16x16x32_bf16 v[102:105], v[208:211], v[180:183], v[102:105]
	v_mfma_f32_16x16x32_bf16 v[98:101], v[234:237], v[180:183], v[98:101]
	v_mfma_f32_16x16x32_bf16 v[86:89], v[208:211], v[188:191], v[86:89]
	v_mfma_f32_16x16x32_bf16 v[82:85], v[234:237], v[188:191], v[82:85]
	v_mfma_f32_16x16x32_bf16 v[70:73], v[208:211], v[200:203], v[70:73]
	v_mfma_f32_16x16x32_bf16 v[66:69], v[234:237], v[200:203], v[66:69]
	s_setprio 0
	s_barrier
; #define PG8_STAGE(bufoff, gbase, voff) do { _Pragma("unroll") for (int _i = 0; _i < 2; ++_i) \
;         __builtin_amdgcn_global_load_lds((const unsigned*)((const char*)(gbase) + (voff)[_i]), (LAS unsigned*)(lds + (bufoff) + ldsw + _i * 8192), 16, 0, 0); } while (0)
; #define PG8_LDA(dst, b, h) do { _Pragma("unroll") for (int m = 0; m < 4; ++m) _Pragma("unroll") for (int k = 0; k < 2; ++k) dst[m][k] = *(const LAS bf16x8*)(lds + PG8_SA(b, h) + aoff + m * 2048 + k * 1024); } while (0)
; #define PG8_MMA(ai, bj, At, Bt) do { __builtin_amdgcn_s_setprio(1); _Pragma("unroll") for (int m = 0; m < 4; ++m) _Pragma("unroll") for (int n = 0; n < 2; ++n) _Pragma("unroll") for (int k = 0; k < 2; ++k) \
;         acc[ai][bj][m][n] = __builtin_amdgcn_mfma_f32_16x16x32_bf16(Bt[n][k], At[m][k], acc[ai][bj][m][n], 0, 0, 0); __builtin_amdgcn_s_setprio(0); } while (0)
; #define PG8_WAIT_V(n) asm volatile("s_waitcnt vmcnt(" #n ")" ::: "memory")
; #define PG8_WAIT_L(n) asm volatile("s_waitcnt lgkmcnt(" #n ")" ::: "memory")
; #define PG8_BAR __builtin_amdgcn_s_barrier()
; #define PG8_SCHED __builtin_amdgcn_sched_barrier(0)
; template <class Epi>
; __device__ __forceinline__ void gemm_phase(LAS unsigned char* lds, const Gemm g, const Sched& S, const Epi& E) {
;     ...
;             PG8_LDA(At, 1, 1); PG8_STAGE(PG8_SA(1, 0), a3, voffA);
;             PG8_BAR; PG8_WAIT_L(0); PG8_MMA(1, 0, At, B0); PG8_BAR; PG8_SCHED;
;             PG8_STAGE(PG8_SB(1, 1), b3 + hstepB, voffB);
;             PG8_WAIT_V(6); PG8_BAR; PG8_MMA(1, 1, At, B1); PG8_BAR;
;         }
	s_add_i32 s69, s70, s51
	v_lshl_add_u64 v[192:193], v[192:193], 0, s[60:61]
	s_mov_b32 m0, s69
	s_nop 0
	global_load_lds_dwordx4 v[192:193], off
	v_lshl_add_u64 v[192:193], v[216:217], 0, s[60:61]
	s_add_i32 m0, s69, 0x2000
	s_nop 0
	global_load_lds_dwordx4 v[192:193], off
	s_mov_b32 m0, s75
	v_lshl_add_u64 v[192:193], v[222:223], 0, s[60:61]
	ds_read_b128 v[168:171], v151 offset:49152
	ds_read_b128 v[172:175], v151 offset:50176
	ds_read_b128 v[176:179], v151 offset:51200
	ds_read_b128 v[180:183], v151 offset:52224
	ds_read_b128 v[184:187], v151 offset:53248
	ds_read_b128 v[188:191], v151 offset:54272
	ds_read_b128 v[196:199], v151 offset:55296
	ds_read_b128 v[200:203], v151 offset:56320
	global_load_lds_dwordx4 v[192:193], off
	v_lshl_add_u64 v[192:193], v[224:225], 0, s[60:61]
	s_mov_b32 m0, s76
	s_nop 0
	global_load_lds_dwordx4 v[192:193], off
	s_add_i32 s68, s68, s51
	v_lshl_add_u64 v[192:193], v[226:227], 0, s[60:61]
	s_mov_b32 m0, s68
	s_nop 0
	global_load_lds_dwordx4 v[192:193], off
	v_lshl_add_u64 v[192:193], v[228:229], 0, s[60:61]
	s_add_i32 m0, s68, 0x2000
	s_nop 0
	global_load_lds_dwordx4 v[192:193], off
	s_waitcnt vmcnt(8)
	s_waitcnt lgkmcnt(0)
	v_mfma_f32_16x16x32_bf16 v[62:65], v[152:155], v[168:171], v[62:65]
	v_mfma_f32_16x16x32_bf16 v[58:61], v[160:163], v[168:171], v[58:61]
	v_mfma_f32_16x16x32_bf16 v[46:49], v[152:155], v[176:179], v[46:49]
	v_mfma_f32_16x16x32_bf16 v[42:45], v[160:163], v[176:179], v[42:45]
	s_barrier
	s_setprio 1
	v_mfma_f32_16x16x32_bf16 v[30:33], v[152:155], v[184:187], v[30:33]
	v_mfma_f32_16x16x32_bf16 v[26:29], v[160:163], v[184:187], v[26:29]
	v_mfma_f32_16x16x32_bf16 v[14:17], v[152:155], v[196:199], v[14:17]
	v_mfma_f32_16x16x32_bf16 v[10:13], v[160:163], v[196:199], v[10:13]
	v_mfma_f32_16x16x32_bf16 v[62:65], v[156:159], v[172:175], v[62:65]
	v_mfma_f32_16x16x32_bf16 v[58:61], v[164:167], v[172:175], v[58:61]
	v_mfma_f32_16x16x32_bf16 v[46:49], v[156:159], v[180:183], v[46:49]
	v_mfma_f32_16x16x32_bf16 v[42:45], v[164:167], v[180:183], v[42:45]
	v_mfma_f32_16x16x32_bf16 v[30:33], v[156:159], v[188:191], v[30:33]
	v_mfma_f32_16x16x32_bf16 v[26:29], v[164:167], v[188:191], v[26:29]
	v_mfma_f32_16x16x32_bf16 v[14:17], v[156:159], v[200:203], v[14:17]
	v_mfma_f32_16x16x32_bf16 v[10:13], v[164:167], v[200:203], v[10:13]
	v_mfma_f32_16x16x32_bf16 v[54:57], v[204:207], v[168:171], v[54:57]
	v_mfma_f32_16x16x32_bf16 v[50:53], v[212:215], v[168:171], v[50:53]
	v_mfma_f32_16x16x32_bf16 v[38:41], v[204:207], v[176:179], v[38:41]
	v_mfma_f32_16x16x32_bf16 v[34:37], v[212:215], v[176:179], v[34:37]
	v_mfma_f32_16x16x32_bf16 v[22:25], v[204:207], v[184:187], v[22:25]
	v_mfma_f32_16x16x32_bf16 v[18:21], v[212:215], v[184:187], v[18:21]
	v_mfma_f32_16x16x32_bf16 v[6:9], v[204:207], v[196:199], v[6:9]
	v_mfma_f32_16x16x32_bf16 v[2:5], v[212:215], v[196:199], v[2:5]
	v_mfma_f32_16x16x32_bf16 v[54:57], v[208:211], v[172:175], v[54:57]
	v_mfma_f32_16x16x32_bf16 v[50:53], v[234:237], v[172:175], v[50:53]
	v_mfma_f32_16x16x32_bf16 v[38:41], v[208:211], v[180:183], v[38:41]
	v_mfma_f32_16x16x32_bf16 v[34:37], v[234:237], v[180:183], v[34:37]
	v_mfma_f32_16x16x32_bf16 v[22:25], v[208:211], v[188:191], v[22:25]
	v_mfma_f32_16x16x32_bf16 v[18:21], v[234:237], v[188:191], v[18:21]
	v_mfma_f32_16x16x32_bf16 v[6:9], v[208:211], v[200:203], v[6:9]
	v_mfma_f32_16x16x32_bf16 v[2:5], v[234:237], v[200:203], v[2:5]
	s_setprio 0
	s_add_u32 s4, s4, 0x100
	s_addc_u32 s5, s5, 0
	s_add_u32 s84, s84, 0x100
	s_addc_u32 s85, s85, 0
	s_cmp_ge_u32 s86, s73
	s_mov_b32 s68, s86
	s_barrier
	s_cbranch_scc0 .LBB0_825
; __device__ __forceinline__ float silu_f(float x) { return x * __builtin_amdgcn_rcpf(1.f + __builtin_amdgcn_exp2f(-LOG2E * x)); }
; __device__ __forceinline__ float pre_get(const Pre& p, int ai, int m, int fr) { return __shfl(p.v[ai], m * 16 + fr); }
; __device__ __forceinline__ float rstd_pre(const float* ss, float v) { return ss ? rsqrtf(v * (1.0f / 2048.0f) + 1e-6f) : 1.0f; }
; #define PG8_BAR __builtin_amdgcn_s_barrier()
; template <class Epi>
; __device__ __forceinline__ void gemm_phase(LAS unsigned char* lds, const Gemm g, const Sched& S, const Epi& E) {
;     ...
;     if (wr == 0) PG8_BAR;
;     PG8_BAR;
;     __device__ __forceinline__ void operator()(const Acc& acc, const Unit& u, int wr, int wc, int fr, int fq, const Pre& pre) const {
;         const int row0 = u.pm * 256 + wr * 64 + fr, col0 = u.pn * 128 + wc * 32 + 8 * fq;
;         float rsq[2][4];
; #pragma unroll
;         for (int ai = 0; ai < 2; ++ai)
; #pragma unroll
;             for (int m = 0; m < 4; ++m) rsq[ai][m] = rstd_pre(ss, pre_get(pre, ai, m, fr));
; #pragma unroll
;         for (int ai = 0; ai < 2; ++ai)
; #pragma unroll
;             for (int m = 0; m < 4; ++m) {
;                 f32x4 v0, v1; const float rs = rsq[ai][m];
; #pragma unroll
;                 for (int e = 0; e < 4; ++e) { v0[e] = silu_f(acc[ai][0][m][0][e] * rs) * (acc[ai][1][m][0][e] * rs); v1[e] = silu_f(acc[ai][0][m][1][e] * rs) * (acc[ai][1][m][1][e] * rs); }
	v_and_or_b32 v144, v220, 64, v141
	v_lshlrev_b32_e32 v160, 2, v144
	ds_bpermute_b32 v155, v160, v142
	ds_bpermute_b32 v154, v160, v142 offset:64
	s_mov_b32 s4, 0x358637bd
	v_mov_b64_e32 v[156:157], s[4:5]
	s_mov_b32 s8, 0x3a000000
	v_lshl_add_u32 v153, s81, 8, v143
	s_waitcnt lgkmcnt(0)
	v_pk_fma_f32 v[158:159], v[154:155], s[8:9], v[156:157] op_sel_hi:[1,0,0]
	s_mov_b32 s81, s80
	v_mul_f32_e32 v144, 0x4b800000, v159
	v_cmp_gt_f32_e64 s[4:5], s97, v159
	v_cmp_gt_f32_e32 vcc, s97, v158
	s_mov_b64 s[68:69], s[66:67]
	v_cndmask_b32_e64 v144, v159, v144, s[4:5]
	v_rsq_f32_e32 v144, v144
	ds_bpermute_b32 v159, v160, v142 offset:128
	v_mul_f32_e32 v146, 0x45800000, v144
	v_cndmask_b32_e64 v144, v144, v146, s[4:5]
	v_cndmask_b32_e64 v154, v144, 1.0, s[34:35]
	v_mul_f32_e32 v144, 0x4b800000, v158
	v_cndmask_b32_e32 v144, v158, v144, vcc
	ds_bpermute_b32 v158, v160, v142 offset:192
	v_rsq_f32_e32 v144, v144
	s_waitcnt lgkmcnt(0)
	v_pk_fma_f32 v[158:159], v[158:159], s[8:9], v[156:157] op_sel_hi:[1,0,0]
	s_nop 0
	v_mul_f32_e32 v142, 0x4b800000, v159
	v_cmp_gt_f32_e64 s[4:5], s97, v159
	v_mul_f32_e32 v146, 0x45800000, v144
	v_cndmask_b32_e32 v144, v144, v146, vcc
	v_cndmask_b32_e64 v142, v159, v142, s[4:5]
	v_rsq_f32_e32 v142, v142
	v_cndmask_b32_e64 v152, v144, 1.0, s[34:35]
	v_cmp_gt_f32_e32 vcc, s97, v158
	ds_bpermute_b32 v159, v160, v140
	v_mul_f32_e32 v144, 0x45800000, v142
	v_cndmask_b32_e64 v142, v142, v144, s[4:5]
	v_cndmask_b32_e64 v150, v142, 1.0, s[34:35]
	v_mul_f32_e32 v142, 0x4b800000, v158
	v_cndmask_b32_e32 v142, v158, v142, vcc
	v_rsq_f32_e32 v142, v142
	ds_bpermute_b32 v158, v160, v140 offset:64
	v_pk_mul_f32 v[110:111], v[110:111], v[152:153] op_sel_hi:[1,0]
	v_pk_mul_f32 v[102:103], v[102:103], v[152:153] op_sel_hi:[1,0]
	v_mul_f32_e32 v144, 0x45800000, v142
	v_cndmask_b32_e32 v142, v142, v144, vcc
	s_waitcnt lgkmcnt(0)
	v_pk_fma_f32 v[158:159], v[158:159], s[8:9], v[156:157] op_sel_hi:[1,0,0]
	v_cndmask_b32_e64 v148, v142, 1.0, s[34:35]
	v_mul_f32_e32 v142, 0x4b800000, v159
	v_cmp_gt_f32_e64 s[4:5], s97, v159
	v_cmp_gt_f32_e32 vcc, s97, v158
	v_pk_mul_f32 v[106:107], v[106:107], v[152:153] op_sel_hi:[1,0]
	v_cndmask_b32_e64 v142, v159, v142, s[4:5]
	v_rsq_f32_e32 v142, v142
	ds_bpermute_b32 v159, v160, v140 offset:128
	v_pk_mul_f32 v[98:99], v[98:99], v[152:153] op_sel_hi:[1,0]
	v_pk_mul_f32 v[104:105], v[104:105], v[152:153] op_sel_hi:[1,0]
	v_mul_f32_e32 v144, 0x45800000, v142
	v_cndmask_b32_e64 v142, v142, v144, s[4:5]
	v_cndmask_b32_e64 v146, v142, 1.0, s[34:35]
	v_mul_f32_e32 v142, 0x4b800000, v158
	v_cndmask_b32_e32 v142, v158, v142, vcc
	ds_bpermute_b32 v158, v160, v140 offset:192
	v_rsq_f32_e32 v142, v142
	v_pk_mul_f32 v[100:101], v[100:101], v[152:153] op_sel_hi:[1,0]
	v_pk_mul_f32 v[94:95], v[94:95], v[150:151] op_sel_hi:[1,0]
	v_pk_mul_f32 v[86:87], v[86:87], v[150:151] op_sel_hi:[1,0]
	s_waitcnt lgkmcnt(0)
	v_pk_fma_f32 v[156:157], v[158:159], s[8:9], v[156:157] op_sel_hi:[1,0,0]
	v_mul_f32_e32 v144, 0x45800000, v142
	v_mul_f32_e32 v140, 0x4b800000, v157
	v_cmp_gt_f32_e64 s[4:5], s97, v157
	v_cndmask_b32_e32 v142, v142, v144, vcc
	v_cndmask_b32_e64 v144, v142, 1.0, s[34:35]
	v_cndmask_b32_e64 v140, v157, v140, s[4:5]
	v_rsq_f32_e32 v140, v140
	v_cmp_gt_f32_e32 vcc, s97, v156
	v_pk_mul_f32 v[90:91], v[90:91], v[150:151] op_sel_hi:[1,0]
	v_pk_mul_f32 v[82:83], v[82:83], v[150:151] op_sel_hi:[1,0]
	v_mul_f32_e32 v142, 0x45800000, v140
	v_cndmask_b32_e64 v140, v140, v142, s[4:5]
	v_cndmask_b32_e64 v142, v140, 1.0, s[34:35]
	v_mul_f32_e32 v140, 0x4b800000, v156
	v_cndmask_b32_e32 v140, v156, v140, vcc
	v_rsq_f32_e32 v140, v140
	v_lshl_or_b32 v156, s55, 7, v149
	v_ashrrev_i32_e32 v157, 31, v156
	v_pk_mul_f32 v[88:89], v[88:89], v[150:151] op_sel_hi:[1,0]
	v_mul_f32_e32 v155, 0x45800000, v140
	v_pk_mul_f32 v[126:127], v[126:127], v[154:155] op_sel_hi:[1,0]
	v_cndmask_b32_e32 v140, v140, v155, vcc
	v_mul_f32_e32 v155, 0xbfb8aa3b, v126
	v_exp_f32_e32 v155, v155
	v_pk_mul_f32 v[84:85], v[84:85], v[150:151] op_sel_hi:[1,0]
	v_pk_mul_f32 v[78:79], v[78:79], v[148:149] op_sel_hi:[1,0]
	v_pk_mul_f32 v[70:71], v[70:71], v[148:149] op_sel_hi:[1,0]
	v_add_f32_e32 v155, 1.0, v155
	v_rcp_f32_e32 v158, v155
	v_mul_f32_e32 v155, 0xbfb8aa3b, v127
	v_exp_f32_e32 v155, v155
	v_pk_mul_f32 v[74:75], v[74:75], v[148:149] op_sel_hi:[1,0]
	v_pk_mul_f32 v[66:67], v[66:67], v[148:149] op_sel_hi:[1,0]
	v_pk_mul_f32 v[72:73], v[72:73], v[148:149] op_sel_hi:[1,0]
	v_add_f32_e32 v155, 1.0, v155
	v_rcp_f32_e32 v159, v155
	v_pk_mul_f32 v[118:119], v[118:119], v[154:155] op_sel_hi:[1,0]
	v_pk_mul_f32 v[122:123], v[122:123], v[154:155] op_sel_hi:[1,0]
	v_readfirstlane_b32 s98, v219
	s_nop 1
	s_bitcmp1_b32 s98, 8
	s_cbranch_scc1 .Lresync_x_825_p
	s_barrier
	s_branch .Lresync_x_825
